# kv-projection task (the loop that runs at 256 blocks): loop-invariant rms-norm gain and key-gain vectors loaded once before the task loop instead of ~18 serialised load-wait-use steps per task
# speedup vs baseline: 1.0250x; 1.0042x over previous
; __device__ __forceinline__ void kvproj_task(int t, int l, const float* kvnorm, const float* kgain, const bf16_t* P, const bf16_t* WUKV, bf16_t* KB, bf16_t* VT, int fr, int fq) {
;     const int h = t & 3, row0 = (t >> 2) * 32 + fr; const bool isc = row0 >= ML;
;     bf16x8 bfr[2][4]; f32x4 kr[2][2]; float skr[2];
; #pragma unroll
;     for (int tb = 0; tb < 2; ++tb) { const int row = row0 + tb * 16; float ss = 0.f; u32x4 raw[4];
; #pragma unroll
;         for (int ks = 0; ks < 4; ++ks) { raw[ks] = ld8(P + (size_t)row * INP + ks * 32 + fq * 8); UNPK8(raw[ks], x);
;             ss += (x[0] * x[0] + x[1] * x[1]) + (x[2] * x[2] + x[3] * x[3]) + (x[4] * x[4] + x[5] * x[5]) + (x[6] * x[6] + x[7] * x[7]); }
; #pragma unroll
;         for (int cbr = 0; cbr < 2; ++cbr) { const u32x2 w = ld4(P + (size_t)row * INP + OFF_KROPE + cbr * 16 + fq * 4); kr[tb][cbr] = (f32x4){bflo(w.x), bfhi(w.x), bflo(w.y), bfhi(w.y)}; }
;         ss += __shfl_xor(ss, 16); ss += __shfl_xor(ss, 32);
;         const float rinv = rsqrtf(ss * (1.f / 128.f) + EPS);
; #pragma unroll
;         for (int ks = 0; ks < 4; ++ks) { const float* gp = kvnorm + l * 128 + ks * 32 + fq * 8; const f32x4 g0 = *(const f32x4*)gp, g1 = *(const f32x4*)(gp + 4); UNPK8(raw[ks], x); u32x4 o;
;             o.x = cvt_pk_bf16(x[0] * rinv * g0[0], x[1] * rinv * g0[1]); o.y = cvt_pk_bf16(x[2] * rinv * g0[2], x[3] * rinv * g0[3]);
;             o.z = cvt_pk_bf16(x[4] * rinv * g1[0], x[5] * rinv * g1[1]); o.w = cvt_pk_bf16(x[6] * rinv * g1[2], x[7] * rinv * g1[3]);
;             bfr[tb][ks] = asfrag(o); }
;         skr[tb] = (kr[tb][0][0] * kr[tb][0][0] + kr[tb][0][1] * kr[tb][0][1]) + (kr[tb][0][2] * kr[tb][0][2] + kr[tb][0][3] * kr[tb][0][3]) + (kr[tb][1][0] * kr[tb][1][0] + kr[tb][1][1] * kr[tb][1][1]) + (kr[tb][1][2] * kr[tb][1][2] + kr[tb][1][3] * kr[tb][1][3]); }
;     const bf16_t* wk0 = WUKV + ((size_t)l * 512 + h * 128 + fr) * 128 + fq * 8;
;     bf16x8 wf[2][4];
; #pragma unroll
;     for (int ks = 0; ks < 4; ++ks) wf[0][ks] = asfrag(ld8(wk0 + ks * 32));
;     f32x4 acc[2][8];
; #pragma unroll
;     for (int cb = 0; cb < 8; ++cb) { acc[0][cb] = (f32x4){0.f, 0.f, 0.f, 0.f}; acc[1][cb] = acc[0][cb];
;         const int nrow = cb < 7 ? (cb + 1) * 16 : 0;
; #pragma unroll
;         for (int ks = 0; ks < 4; ++ks) wf[(cb + 1) & 1][ks] = asfrag(ld8(wk0 + (size_t)nrow * 128 + ks * 32));
.LBB0_419:
	s_mov_b64 s[42:43], s[72:73]
	v_mov_b32 v0, v194
	v_readlane_b32 s6, v253, 4
	v_readfirstlane_b32 s20, v0
	s_ashr_i32 s1, s20, 6
	v_readlane_b32 s7, v253, 5
	s_add_i32 s21, s1, s69
	v_and_b32_e32 v97, 15, v0
	v_bfe_u32 v214, v0, 4, 2
	s_mov_b64 s[4:5], -1
	s_and_b64 vcc, exec, s[6:7]
	s_cbranch_vccz .LBB0_424
	s_cmpk_gt_i32 s21, 0x8ff
	s_movk_i32 s14, 0xc0
	s_mov_b32 s15, 0x12000
	s_mov_b32 s18, 0x14000
	s_movk_i32 s19, 0x1000
	s_movk_i32 s23, 0x3000
	s_mov_b32 s24, 0x13000
	s_mov_b32 s25, 0x15000
	s_mov_b32 s26, 0x24000
	s_mov_b32 s27, 0x25000
	s_mov_b32 s44, 0x26000
	s_mov_b32 s45, 0x27000
	s_mov_b32 s46, 0x36000
	s_mov_b32 s48, 0x37000
	s_mov_b32 s51, 0x38000
	s_mov_b32 s52, 0x39000
	s_cbranch_scc1 .LBB0_423
	v_and_b32_e32 v5, 64, v199
	v_xor_b32_e32 v4, 16, v199
	v_add_u32_e32 v5, 64, v5
	v_cmp_lt_i32_e32 vcc, v4, v5
	v_readlane_b32 s6, v254, 27
	v_readlane_b32 s7, v254, 28
	v_cndmask_b32_e32 v4, v199, v4, vcc
	v_lshlrev_b32_e32 v215, 2, v4
	v_xor_b32_e32 v4, 32, v199
	v_cmp_lt_i32_e32 vcc, v4, v5
	v_mov_b32_e32 v5, v1
	s_add_u32 s4, s42, 0x8eb8000
	v_cndmask_b32_e32 v4, v199, v4, vcc
	v_lshlrev_b32_e32 v216, 2, v4
	v_lshlrev_b32_e32 v4, 5, v214
	v_lshl_add_u64 v[98:99], s[6:7], 0, v[4:5]
	v_readlane_b32 s6, v254, 30
	s_addc_u32 s5, s43, 0
	v_lshlrev_b32_e32 v0, 3, v214
	v_lshlrev_b32_e32 v2, 4, v214
	v_mov_b32_e32 v3, v1
	v_readlane_b32 s7, v254, 31
	v_lshl_add_u64 v[94:95], s[4:5], 0, v[2:3]
	v_lshlrev_b32_e32 v96, 2, v214
	v_lshl_add_u64 v[4:5], s[42:43], 0, v[2:3]
	v_lshl_add_u64 v[100:101], s[6:7], 0, v[2:3]
	v_lshl_add_u64 v[2:3], s[42:43], 0, v[0:1]
	s_mov_b64 s[6:7], 0x7838000
	v_lshl_add_u64 v[102:103], v[2:3], 0, s[6:7]
	v_and_b32_e32 v2, 4, v96
	v_cvt_f32_ubyte0_e32 v3, v2
	v_mul_f32_e32 v3, 0xbfd49a78, v3
	v_exp_f32_e32 v217, v3
	v_or_b32_e32 v3, 1, v2
	v_cvt_f32_ubyte0_e32 v3, v3
	s_add_u32 s40, s42, 0x85b8000
	v_mul_f32_e32 v3, 0xbfd49a78, v3
	s_addc_u32 s41, s43, 0
	v_exp_f32_e32 v218, v3
	v_or_b32_e32 v3, 2, v2
	v_or_b32_e32 v2, 3, v2
	s_bfe_u32 s22, s20, 0x20006
	v_cvt_f32_ubyte0_e32 v2, v2
	s_lshl_b32 s6, s22, 7
	v_readlane_b32 s7, v254, 29
	v_cvt_f32_ubyte0_e32 v3, v3
	v_mul_f32_e32 v2, 0xbfd49a78, v2
	s_or_b32 s6, s7, s6
	v_mul_f32_e32 v3, 0xbfd49a78, v3
	v_exp_f32_e32 v220, v2
	v_or_b32_e32 v2, s6, v97
	v_exp_f32_e32 v219, v3
	v_lshlrev_b32_e32 v2, 7, v2
	v_mov_b32_e32 v3, v1
	v_lshl_add_u64 v[2:3], v[2:3], 1, v[4:5]
	s_mov_b64 s[6:7], 0x2260000
	v_lshl_add_u64 v[104:105], v[2:3], 0, s[6:7]
	s_mov_b64 s[6:7], 0x2261000
	v_lshl_add_u64 v[106:107], v[2:3], 0, s[6:7]
	s_mov_b64 s[6:7], 0x2261040
	v_lshl_add_u64 v[108:109], v[2:3], 0, s[6:7]
	s_mov_b64 s[6:7], 0x2261080
	v_lshl_add_u64 v[110:111], v[2:3], 0, s[6:7]
	s_mov_b64 s[6:7], 0x22610c0
	v_lshl_add_u64 v[112:113], v[2:3], 0, s[6:7]
	s_mov_b64 s[6:7], 0x2262000
	v_lshl_add_u64 v[114:115], v[2:3], 0, s[6:7]
	s_mov_b64 s[6:7], 0x2262040
	v_lshl_add_u64 v[116:117], v[2:3], 0, s[6:7]
	s_mov_b64 s[6:7], 0x2262080
	v_lshl_add_u64 v[118:119], v[2:3], 0, s[6:7]
	s_mov_b64 s[6:7], 0x22620c0
	v_lshl_add_u64 v[120:121], v[2:3], 0, s[6:7]
	s_mov_b64 s[6:7], 0x2263000
	v_lshl_add_u64 v[122:123], v[2:3], 0, s[6:7]
	s_mov_b64 s[6:7], 0x2263040
	v_lshl_add_u64 v[124:125], v[2:3], 0, s[6:7]
	s_mov_b64 s[6:7], 0x2263080
	v_lshl_add_u64 v[126:127], v[2:3], 0, s[6:7]
	s_mov_b64 s[6:7], 0x22630c0
	v_lshl_add_u64 v[128:129], v[2:3], 0, s[6:7]
	s_mov_b64 s[6:7], 0x2264000
	v_lshl_add_u64 v[130:131], v[2:3], 0, s[6:7]
	s_mov_b64 s[6:7], 0x2264040
	v_lshl_add_u64 v[132:133], v[2:3], 0, s[6:7]
	s_mov_b64 s[6:7], 0x2264080
	v_lshl_add_u64 v[134:135], v[2:3], 0, s[6:7]
	s_mov_b64 s[6:7], 0x22640c0
	v_lshl_add_u64 v[136:137], v[2:3], 0, s[6:7]
	s_mov_b64 s[6:7], 0x2265000
	v_lshl_add_u64 v[138:139], v[2:3], 0, s[6:7]
	s_mov_b64 s[6:7], 0x2265040
	v_lshl_add_u64 v[140:141], v[2:3], 0, s[6:7]
	s_mov_b64 s[6:7], 0x2265080
	v_lshl_add_u64 v[142:143], v[2:3], 0, s[6:7]
	s_mov_b64 s[6:7], 0x22650c0
	v_lshl_add_u64 v[144:145], v[2:3], 0, s[6:7]
	s_mov_b64 s[6:7], 0x2266000
	v_lshl_add_u64 v[146:147], v[2:3], 0, s[6:7]
	s_mov_b64 s[6:7], 0x2266040
	v_lshl_add_u64 v[148:149], v[2:3], 0, s[6:7]
	s_mov_b64 s[6:7], 0x2266080
	v_lshl_add_u64 v[156:157], v[2:3], 0, s[6:7]
	s_mov_b64 s[6:7], 0x22660c0
	v_lshl_add_u64 v[158:159], v[2:3], 0, s[6:7]
	s_mov_b64 s[6:7], 0x2267000
	v_lshl_add_u64 v[160:161], v[2:3], 0, s[6:7]
	s_mov_b64 s[6:7], 0x2267040
	v_lshl_add_u64 v[162:163], v[2:3], 0, s[6:7]
	s_mov_b64 s[6:7], 0x2267080
	v_lshl_add_u64 v[164:165], v[2:3], 0, s[6:7]
	s_mov_b64 s[6:7], 0x22670c0
	v_lshl_add_u64 v[168:169], s[4:5], 0, v[0:1]
	s_lshl_b32 s1, s1, 3
	v_readlane_b32 s4, v253, 10
	v_cmp_gt_u32_e64 s[36:37], 2, v214
	v_lshl_add_u64 v[166:167], v[2:3], 0, s[6:7]
	s_add_i32 s4, s4, s1
	s_mov_b32 s5, s21
; __device__ __forceinline__ unsigned cvt_pk_bf16(float lo, float hi) { unsigned r; asm volatile("v_cvt_pk_bf16_f32 %0, %1, %2" : "=v"(r) : "v"(lo), "v"(hi)); return r; }
; __device__ __forceinline__ float bflo(unsigned w) { return __uint_as_float(w << 16); }
; __device__ __forceinline__ float bfhi(unsigned w) { return __uint_as_float(w & 0xffff0000u); }
; #define UNPK8(VV_, XX_) float XX_[8] = {bflo((VV_).x), bfhi((VV_).x), bflo((VV_).y), bfhi((VV_).y), bflo((VV_).z), bfhi((VV_).z), bflo((VV_).w), bfhi((VV_).w)}
; __device__ __forceinline__ void kvproj_task(int t, int l, const float* kvnorm, const float* kgain, const bf16_t* P, const bf16_t* WUKV, bf16_t* KB, bf16_t* VT, int fr, int fq) {
;     ...
;     for (int tb = 0; tb < 2; ++tb) { const int row = row0 + tb * 16; float ss = 0.f; u32x4 raw[4];
; #pragma unroll
;         for (int ks = 0; ks < 4; ++ks) { raw[ks] = ld8(P + (size_t)row * INP + ks * 32 + fq * 8); UNPK8(raw[ks], x);
;             ss += (x[0] * x[0] + x[1] * x[1]) + (x[2] * x[2] + x[3] * x[3]) + (x[4] * x[4] + x[5] * x[5]) + (x[6] * x[6] + x[7] * x[7]); }
; #pragma unroll
;         for (int cbr = 0; cbr < 2; ++cbr) { const u32x2 w = ld4(P + (size_t)row * INP + OFF_KROPE + cbr * 16 + fq * 4); kr[tb][cbr] = (f32x4){bflo(w.x), bfhi(w.x), bflo(w.y), bfhi(w.y)}; }
;         ss += __shfl_xor(ss, 16); ss += __shfl_xor(ss, 32);
;         const float rinv = rsqrtf(ss * (1.f / 128.f) + EPS);
; #pragma unroll
;         for (int ks = 0; ks < 4; ++ks) { const float* gp = kvnorm + l * 128 + ks * 32 + fq * 8; const f32x4 g0 = *(const f32x4*)gp, g1 = *(const f32x4*)(gp + 4); UNPK8(raw[ks], x); u32x4 o;
;             o.x = cvt_pk_bf16(x[0] * rinv * g0[0], x[1] * rinv * g0[1]); o.y = cvt_pk_bf16(x[2] * rinv * g0[2], x[3] * rinv * g0[3]);
;             o.z = cvt_pk_bf16(x[4] * rinv * g1[0], x[5] * rinv * g1[1]); o.w = cvt_pk_bf16(x[6] * rinv * g1[2], x[7] * rinv * g1[3]);
;             bfr[tb][ks] = asfrag(o); }
.LBB0_422:
	s_and_b32 s1, s4, 0xffffffe0
	v_or_b32_e32 v171, s1, v97
	v_mad_i64_i32 v[6:7], s[6:7], v171, s84, v[94:95]
	flat_load_dwordx4 v[14:17], v[6:7]
	flat_load_dwordx4 v[2:5], v[6:7] offset:64
	flat_load_dwordx4 v[40:43], v[6:7] offset:128
	flat_load_dwordx4 v[50:53], v[6:7] offset:192
	v_or_b32_e32 v173, 16, v171
	s_add_i32 s5, s5, s60
	s_add_i32 s4, s4, s75
	s_cmpk_gt_i32 s5, 0x8ff
	s_waitcnt vmcnt(0) lgkmcnt(0)
	v_and_b32_e32 v37, 0xffff0000, v15
	v_and_b32_e32 v25, 0xffff0000, v3
	v_and_b32_e32 v24, 0xffff0000, v2
	v_lshlrev_b32_e32 v27, 16, v3
	v_lshlrev_b32_e32 v26, 16, v2
	v_pk_mul_f32 v[2:3], v[24:25], v[24:25]
	v_and_b32_e32 v21, 0xffff0000, v5
	v_and_b32_e32 v20, 0xffff0000, v4
	v_pk_fma_f32 v[2:3], v[26:27], v[26:27], v[2:3]
	v_lshlrev_b32_e32 v23, 16, v5
	v_lshlrev_b32_e32 v22, 16, v4
	v_pk_mul_f32 v[4:5], v[20:21], v[20:21]
	v_pk_add_f32 v[2:3], v[2:3], v[2:3] op_sel:[0,1] op_sel_hi:[1,0]
	v_pk_fma_f32 v[34:35], v[22:23], v[22:23], v[4:5]
	v_and_b32_e32 v39, 0xffff0000, v14
	v_pk_add_f32 v[44:45], v[34:35], v[2:3]
	v_mad_i64_i32 v[2:3], s[6:7], v171, s84, v[168:169]
	flat_load_dwordx2 v[4:5], v[2:3] offset:256
	s_nop 0
	flat_load_dwordx2 v[2:3], v[2:3] offset:288
	v_and_b32_e32 v38, 0xffff0000, v16
	v_lshlrev_b32_e32 v36, 16, v15
	v_mul_f32_e32 v0, v37, v37
	v_lshlrev_b32_e32 v18, 16, v40
	v_and_b32_e32 v19, 0xffff0000, v40
	v_lshlrev_b32_e32 v8, 16, v41
	v_and_b32_e32 v9, 0xffff0000, v41
	v_lshlrev_b32_e32 v41, 16, v14
	v_lshlrev_b32_e32 v40, 16, v16
	v_pk_mul_f32 v[14:15], v[38:39], v[38:39]
	v_pk_fma_f32 v[28:29], v[36:37], v[36:37], v[0:1] op_sel_hi:[1,1,0]
	v_lshlrev_b32_e32 v7, 16, v53
	v_pk_fma_f32 v[14:15], v[40:41], v[40:41], v[14:15]
	v_mul_f32_e32 v6, v19, v19
	v_lshlrev_b32_e32 v32, 16, v17
	v_and_b32_e32 v33, 0xffff0000, v17
	v_lshlrev_b32_e32 v48, 16, v51
	v_and_b32_e32 v47, 0xffff0000, v51
	v_pk_add_f32 v[16:17], v[14:15], v[28:29] op_sel:[1,0] op_sel_hi:[0,1]
	v_lshlrev_b32_e32 v31, 16, v50
	v_and_b32_e32 v29, 0xffff0000, v50
	v_pk_fma_f32 v[50:51], v[18:19], v[18:19], v[6:7] op_sel_hi:[1,1,0]
	v_mul_f32_e32 v6, v9, v9
	v_and_b32_e32 v0, 0xffff0000, v53
	v_mul_f32_e32 v46, v48, v48
	v_mul_f32_e32 v49, v47, v47
	v_pk_add_f32 v[54:55], v[14:15], v[16:17]
	v_and_b32_e32 v28, 0xffff0000, v42
	v_pk_mov_b32 v[14:15], v[42:43], v[52:53] op_sel:[1,0]
	v_lshlrev_b32_e32 v17, 16, v52
	v_pk_fma_f32 v[52:53], v[8:9], v[8:9], v[6:7] op_sel_hi:[1,1,0]
	v_lshlrev_b32_e32 v30, 16, v42
	v_lshlrev_b32_e32 v16, 16, v43
	v_pk_mul_f32 v[42:43], v[28:29], v[28:29]
	v_mov_b32_e32 v51, v46
	v_mov_b32_e32 v53, v49
	v_and_b32_e32 v15, 0xffff0000, v15
	v_and_b32_e32 v14, 0xffff0000, v14
	v_pk_fma_f32 v[42:43], v[30:31], v[30:31], v[42:43]
	v_pk_add_f32 v[50:51], v[50:51], v[52:53]
	v_mul_f32_e32 v6, v33, v33
	v_pk_add_f32 v[42:43], v[42:43], v[50:51]
	v_pk_mul_f32 v[50:51], v[14:15], v[14:15]
	v_mov_b32_e32 v52, v54
	v_pk_fma_f32 v[50:51], v[16:17], v[16:17], v[50:51]
	v_mov_b32_e32 v53, v7
	v_pk_add_f32 v[42:43], v[50:51], v[42:43]
	v_pk_fma_f32 v[50:51], v[32:33], v[32:33], v[6:7] op_sel_hi:[1,1,0]
	v_mul_f32_e32 v56, v0, v0
	v_mov_b32_e32 v6, v50
	v_pk_add_f32 v[50:51], v[50:51], v[54:55]
	v_pk_mul_f32 v[52:53], v[6:7], v[52:53]
	v_pk_add_f32 v[34:35], v[34:35], v[44:45] op_sel:[1,0] op_sel_hi:[0,1]
	v_mov_b32_e32 v51, v53
	v_mov_b32_e32 v35, v56
	v_pk_add_f32 v[34:35], v[50:51], v[34:35]
	s_waitcnt vmcnt(0) lgkmcnt(0)
	v_and_b32_e32 v189, 0xffff0000, v5
	v_pk_add_f32 v[34:35], v[34:35], v[42:43]
	s_nop 0
	s_nop 0
	s_nop 0
	s_nop 0
	v_lshlrev_b32_e32 v174, 16, v3
	v_and_b32_e32 v176, 0xffff0000, v3
	v_add_f32_e32 v3, v34, v35
	ds_bpermute_b32 v6, v215, v3
	v_and_b32_e32 v188, 0xffff0000, v4
	v_lshlrev_b32_e32 v187, 16, v5
	v_lshlrev_b32_e32 v186, 16, v4
	v_pk_mul_f32 v[4:5], v[188:189], v[188:189]
	s_waitcnt lgkmcnt(0)
	v_add_f32_e32 v3, v3, v6
	ds_bpermute_b32 v6, v216, v3
	v_pk_fma_f32 v[190:191], v[186:187], v[186:187], v[4:5]
	v_lshlrev_b32_e32 v184, 16, v2
	v_and_b32_e32 v185, 0xffff0000, v2
	s_waitcnt lgkmcnt(0)
	v_add_f32_e32 v3, v3, v6
	v_fmamk_f32 v3, v3, 0x3c000000, v197
	v_cmp_gt_f32_e32 vcc, s47, v3
	v_mul_f32_e32 v6, 0x4b800000, v3
	s_nop 0
	v_cndmask_b32_e32 v3, v3, v6, vcc
	v_rsq_f32_e32 v3, v3
	s_nop 0
	v_mul_f32_e32 v6, 0x45800000, v3
	v_cndmask_b32_e32 v3, v3, v6, vcc
	v_mul_f32_e32 v6, v3, v41
	v_mul_f32_e32 v34, v3, v39
	v_mul_f32_e32 v35, v3, v37
	v_mul_f32_e32 v24, v3, v24
	v_mul_f32_e32 v20, v3, v20
	v_mul_f32_e32 v0, v3, v0
	s_waitcnt vmcnt(0)
	v_mul_f32_e32 v6, v108, v6
	v_mul_f32_e32 v34, v109, v34
	v_cvt_pk_bf16_f32 v34, v6, v34
	v_mul_f32_e32 v6, v3, v36
	v_mul_f32_e32 v6, v110, v6
	v_mul_f32_e32 v35, v111, v35
	v_cvt_pk_bf16_f32 v35, v6, v35
	v_mul_f32_e32 v6, v3, v40
	v_mul_f32_e32 v36, v3, v38
	v_mul_f32_e32 v6, v116, v6
	v_mul_f32_e32 v36, v117, v36
	v_cvt_pk_bf16_f32 v36, v6, v36
	v_mul_f32_e32 v6, v3, v32
	v_mul_f32_e32 v32, v3, v33
	v_mul_f32_e32 v6, v118, v6
	v_mul_f32_e32 v32, v119, v32
	v_cvt_pk_bf16_f32 v37, v6, v32
	s_nop 0
	s_nop 0
	s_nop 0
	s_nop 0
	v_mul_f32_e32 v6, v3, v26
	s_waitcnt vmcnt(1)
	v_mul_f32_e32 v20, v133, v20
	s_waitcnt vmcnt(0)
	v_mul_f32_e32 v6, v124, v6
	v_mul_f32_e32 v24, v125, v24
	v_cvt_pk_bf16_f32 v38, v6, v24
	v_mul_f32_e32 v6, v3, v27
	v_mul_f32_e32 v6, v126, v6
	v_mul_f32_e32 v24, v3, v25
	v_mul_f32_e32 v24, v127, v24
	v_cvt_pk_bf16_f32 v39, v6, v24
	v_mul_f32_e32 v6, v3, v22
	v_mul_f32_e32 v6, v132, v6
	v_cvt_pk_bf16_f32 v40, v6, v20
	v_mul_f32_e32 v20, v3, v21
	v_mul_f32_e32 v6, v3, v23
	v_mul_f32_e32 v20, v135, v20
	v_mul_f32_e32 v6, v134, v6
	v_cvt_pk_bf16_f32 v41, v6, v20
	s_nop 0
	s_nop 0
	s_nop 0
	s_nop 0
	v_mul_f32_e32 v6, v3, v18
	v_mul_f32_e32 v18, v3, v19
	s_waitcnt vmcnt(0)
; __device__ __forceinline__ unsigned cvt_pk_bf16(float lo, float hi) { unsigned r; asm volatile("v_cvt_pk_bf16_f32 %0, %1, %2" : "=v"(r) : "v"(lo), "v"(hi)); return r; }
; __device__ __forceinline__ float bflo(unsigned w) { return __uint_as_float(w << 16); }
; __device__ __forceinline__ float bfhi(unsigned w) { return __uint_as_float(w & 0xffff0000u); }
; #define UNPK8(VV_, XX_) float XX_[8] = {bflo((VV_).x), bfhi((VV_).x), bflo((VV_).y), bfhi((VV_).y), bflo((VV_).z), bfhi((VV_).z), bflo((VV_).w), bfhi((VV_).w)}
; __device__ __forceinline__ void kvproj_task(int t, int l, const float* kvnorm, const float* kgain, const bf16_t* P, const bf16_t* WUKV, bf16_t* KB, bf16_t* VT, int fr, int fq) {
;     ...
;     for (int tb = 0; tb < 2; ++tb) { const int row = row0 + tb * 16; float ss = 0.f; u32x4 raw[4];
; #pragma unroll
;         for (int ks = 0; ks < 4; ++ks) { raw[ks] = ld8(P + (size_t)row * INP + ks * 32 + fq * 8); UNPK8(raw[ks], x);
;             ss += (x[0] * x[0] + x[1] * x[1]) + (x[2] * x[2] + x[3] * x[3]) + (x[4] * x[4] + x[5] * x[5]) + (x[6] * x[6] + x[7] * x[7]); }
; #pragma unroll
;         for (int cbr = 0; cbr < 2; ++cbr) { const u32x2 w = ld4(P + (size_t)row * INP + OFF_KROPE + cbr * 16 + fq * 4); kr[tb][cbr] = (f32x4){bflo(w.x), bfhi(w.x), bflo(w.y), bfhi(w.y)}; }
;         ss += __shfl_xor(ss, 16); ss += __shfl_xor(ss, 32);
;         const float rinv = rsqrtf(ss * (1.f / 128.f) + EPS);
; #pragma unroll
;         for (int ks = 0; ks < 4; ++ks) { const float* gp = kvnorm + l * 128 + ks * 32 + fq * 8; const f32x4 g0 = *(const f32x4*)gp, g1 = *(const f32x4*)(gp + 4); UNPK8(raw[ks], x); u32x4 o;
;             o.x = cvt_pk_bf16(x[0] * rinv * g0[0], x[1] * rinv * g0[1]); o.y = cvt_pk_bf16(x[2] * rinv * g0[2], x[3] * rinv * g0[3]);
;             o.z = cvt_pk_bf16(x[4] * rinv * g1[0], x[5] * rinv * g1[1]); o.w = cvt_pk_bf16(x[6] * rinv * g1[2], x[7] * rinv * g1[3]);
;             bfr[tb][ks] = asfrag(o); }
;         skr[tb] = (kr[tb][0][0] * kr[tb][0][0] + kr[tb][0][1] * kr[tb][0][1]) + (kr[tb][0][2] * kr[tb][0][2] + kr[tb][0][3] * kr[tb][0][3]) + (kr[tb][1][0] * kr[tb][1][0] + kr[tb][1][1] * kr[tb][1][1]) + (kr[tb][1][2] * kr[tb][1][2] + kr[tb][1][3] * kr[tb][1][3]); }
	v_mul_f32_e32 v6, v140, v6
	v_mul_f32_e32 v18, v141, v18
	v_cvt_pk_bf16_f32 v42, v6, v18
	v_mul_f32_e32 v6, v3, v8
	v_mul_f32_e32 v8, v3, v9
	v_mul_f32_e32 v6, v142, v6
	v_mul_f32_e32 v8, v143, v8
	v_cvt_pk_bf16_f32 v43, v6, v8
	v_mul_f32_e32 v6, v3, v30
	v_mul_f32_e32 v8, v3, v28
	v_mul_f32_e32 v6, v162, v6
	v_mul_f32_e32 v8, v163, v8
	v_cvt_pk_bf16_f32 v44, v6, v8
	v_mul_f32_e32 v6, v3, v16
	v_mul_f32_e32 v8, v3, v14
	v_mul_f32_e32 v6, v164, v6
	v_mul_f32_e32 v8, v165, v8
	v_cvt_pk_bf16_f32 v45, v6, v8
	s_nop 0
	s_nop 0
	s_nop 0
	s_nop 0
	v_mul_f32_e32 v6, v3, v31
	v_mul_f32_e32 v8, v3, v29
	s_waitcnt vmcnt(1)
	v_mul_f32_e32 v0, v0, v121
	s_waitcnt vmcnt(0)
	v_mul_f32_e32 v6, v6, v156
	v_mul_f32_e32 v8, v8, v157
	v_cvt_pk_bf16_f32 v46, v6, v8
	v_mul_f32_e32 v6, v3, v48
	v_mul_f32_e32 v6, v6, v158
	v_mul_f32_e32 v8, v3, v47
	v_mul_f32_e32 v8, v8, v159
	v_cvt_pk_bf16_f32 v47, v6, v8
	v_mul_f32_e32 v6, v3, v17
	v_mul_f32_e32 v6, v6, v112
	v_mul_f32_e32 v8, v3, v15
	v_mul_f32_e32 v8, v8, v113
	v_cvt_pk_bf16_f32 v48, v6, v8
	v_mul_f32_e32 v6, v3, v7
	v_mul_f32_e32 v6, v6, v120
	v_mad_i64_i32 v[14:15], s[6:7], v173, s84, v[94:95]
	v_cvt_pk_bf16_f32 v49, v6, v0
	flat_load_dwordx4 v[2:5], v[14:15]
	flat_load_dwordx4 v[6:9], v[14:15] offset:64
	s_waitcnt vmcnt(0) lgkmcnt(0)
	v_and_b32_e32 v33, 0xffff0000, v3
	v_and_b32_e32 v27, 0xffff0000, v7
	v_and_b32_e32 v26, 0xffff0000, v6
	v_lshlrev_b32_e32 v29, 16, v7
	v_lshlrev_b32_e32 v28, 16, v6
	v_pk_mul_f32 v[6:7], v[26:27], v[26:27]
	v_and_b32_e32 v23, 0xffff0000, v9
	v_and_b32_e32 v22, 0xffff0000, v8
	v_pk_fma_f32 v[6:7], v[28:29], v[28:29], v[6:7]
	v_lshlrev_b32_e32 v25, 16, v9
	v_lshlrev_b32_e32 v24, 16, v8
	v_pk_mul_f32 v[8:9], v[22:23], v[22:23]
	v_pk_add_f32 v[6:7], v[6:7], v[6:7] op_sel:[0,1] op_sel_hi:[1,0]
	v_pk_fma_f32 v[50:51], v[24:25], v[24:25], v[8:9]
	v_and_b32_e32 v57, 0xffff0000, v2
	v_pk_add_f32 v[52:53], v[50:51], v[6:7]
	flat_load_dwordx4 v[6:9], v[14:15] offset:128
	v_and_b32_e32 v56, 0xffff0000, v4
	flat_load_dwordx4 v[14:17], v[14:15] offset:192
	v_lshlrev_b32_e32 v32, 16, v3
	v_mul_f32_e32 v0, v33, v33
	v_lshlrev_b32_e32 v59, 16, v2
	v_lshlrev_b32_e32 v58, 16, v4
	v_pk_fma_f32 v[54:55], v[32:33], v[32:33], v[0:1] op_sel_hi:[1,1,0]
	v_lshlrev_b32_e32 v30, 16, v5
	v_and_b32_e32 v31, 0xffff0000, v5
	s_waitcnt vmcnt(0) lgkmcnt(0)
	v_lshlrev_b32_e32 v20, 16, v6
	v_and_b32_e32 v21, 0xffff0000, v6
	v_lshlrev_b32_e32 v18, 16, v7
	v_and_b32_e32 v19, 0xffff0000, v7
	v_mad_i64_i32 v[6:7], s[6:7], v173, s84, v[168:169]
	flat_load_dwordx2 v[68:69], v[6:7] offset:256
	flat_load_dwordx2 v[66:67], v[6:7] offset:288
	v_pk_mul_f32 v[6:7], v[56:57], v[56:57]
	v_and_b32_e32 v0, 0xffff0000, v17
	v_pk_fma_f32 v[6:7], v[58:59], v[58:59], v[6:7]
	v_lshlrev_b32_e32 v73, 16, v15
	v_pk_add_f32 v[54:55], v[6:7], v[54:55] op_sel:[1,0] op_sel_hi:[0,1]
	v_mul_f32_e32 v3, v0, v0
	v_pk_add_f32 v[6:7], v[6:7], v[54:55]
	v_pk_mov_b32 v[54:55], v[8:9], v[16:17] op_sel:[1,0]
	v_mul_f32_e32 v2, v21, v21
	v_and_b32_e32 v72, 0xffff0000, v15
	v_lshlrev_b32_e32 v15, 16, v17
	v_mul_f32_e32 v60, v73, v73
	v_lshlrev_b32_e32 v65, 16, v16
	v_and_b32_e32 v17, 0xffff0000, v55
	v_and_b32_e32 v16, 0xffff0000, v54
	v_pk_fma_f32 v[54:55], v[20:21], v[20:21], v[2:3] op_sel_hi:[1,1,0]
	v_mul_f32_e32 v2, v19, v19
	v_mul_f32_e32 v5, v72, v72
	v_and_b32_e32 v63, 0xffff0000, v14
	v_and_b32_e32 v62, 0xffff0000, v8
	v_mov_b32_e32 v55, v60
	v_pk_fma_f32 v[60:61], v[18:19], v[18:19], v[2:3] op_sel_hi:[1,1,0]
	v_lshlrev_b32_e32 v71, 16, v14
	v_lshlrev_b32_e32 v70, 16, v8
	v_lshlrev_b32_e32 v64, 16, v9
	v_pk_mul_f32 v[8:9], v[62:63], v[62:63]
	v_mov_b32_e32 v61, v5
	v_pk_fma_f32 v[8:9], v[70:71], v[70:71], v[8:9]
	v_pk_add_f32 v[4:5], v[54:55], v[60:61]
	v_mul_f32_e32 v2, v31, v31
	v_pk_add_f32 v[4:5], v[8:9], v[4:5]
	v_pk_mul_f32 v[8:9], v[16:17], v[16:17]
	v_mov_b32_e32 v54, v6
	v_pk_fma_f32 v[8:9], v[64:65], v[64:65], v[8:9]
	v_mov_b32_e32 v55, v15
	v_pk_add_f32 v[4:5], v[8:9], v[4:5]
	v_pk_fma_f32 v[8:9], v[30:31], v[30:31], v[2:3] op_sel_hi:[1,1,0]
	s_waitcnt vmcnt(0) lgkmcnt(0)
	v_and_b32_e32 v183, 0xffff0000, v69
	v_mov_b32_e32 v14, v8
	v_pk_add_f32 v[6:7], v[8:9], v[6:7]
	v_pk_mul_f32 v[8:9], v[14:15], v[54:55]
	v_and_b32_e32 v182, 0xffff0000, v68
	v_mov_b32_e32 v7, v9
	v_pk_add_f32 v[8:9], v[50:51], v[52:53] op_sel:[1,0] op_sel_hi:[0,1]
	v_mov_b32_e32 v9, v3
	v_pk_add_f32 v[2:3], v[6:7], v[8:9]
	v_lshlrev_b32_e32 v181, 16, v69
	v_pk_add_f32 v[2:3], v[2:3], v[4:5]
	v_lshlrev_b32_e32 v180, 16, v68
	v_add_f32_e32 v2, v2, v3
	ds_bpermute_b32 v3, v215, v2
	v_lshlrev_b32_e32 v170, 16, v67
	v_and_b32_e32 v172, 0xffff0000, v67
	v_lshlrev_b32_e32 v178, 16, v66
	v_and_b32_e32 v179, 0xffff0000, v66
	s_waitcnt lgkmcnt(0)
	v_add_f32_e32 v2, v2, v3
	ds_bpermute_b32 v3, v216, v2
	s_waitcnt lgkmcnt(0)
	v_add_f32_e32 v2, v2, v3
	v_fmamk_f32 v2, v2, 0x3c000000, v197
	v_cmp_gt_f32_e32 vcc, s47, v2
	v_mul_f32_e32 v3, 0x4b800000, v2
	s_nop 0
	v_cndmask_b32_e32 v2, v2, v3, vcc
	v_rsq_f32_e32 v2, v2
	s_nop 0
	v_mul_f32_e32 v3, 0x45800000, v2
	v_cndmask_b32_e32 v14, v2, v3, vcc
	s_nop 0
	s_nop 0
	s_nop 0
	s_nop 0
	v_mul_f32_e32 v50, v14, v59
	v_mul_f32_e32 v28, v14, v28
	v_mul_f32_e32 v26, v14, v26
	v_mul_f32_e32 v20, v14, v20
	v_mul_f32_e32 v0, v14, v0
	v_cmp_lt_i32_e32 vcc, s49, v171
	s_waitcnt vmcnt(0)
	v_mul_f32_e32 v6, v108, v50
	v_mul_f32_e32 v50, v14, v57
	v_mul_f32_e32 v7, v109, v50
	v_cvt_pk_bf16_f32 v50, v6, v7
	v_mul_f32_e32 v6, v14, v32
	v_mul_f32_e32 v6, v110, v6
	v_mul_f32_e32 v7, v14, v33
	v_mul_f32_e32 v7, v111, v7
	v_cvt_pk_bf16_f32 v51, v6, v7
	v_mul_f32_e32 v6, v14, v58
	v_mul_f32_e32 v2, v116, v6
	v_mul_f32_e32 v6, v14, v56
	v_mul_f32_e32 v3, v117, v6
	v_cvt_pk_bf16_f32 v52, v2, v3
	v_mul_f32_e32 v2, v14, v30
	v_mul_f32_e32 v3, v14, v31
	v_mul_f32_e32 v2, v118, v2
	v_mul_f32_e32 v3, v119, v3
	v_cvt_pk_bf16_f32 v53, v2, v3
	s_nop 0
	s_nop 0
	s_nop 0
	s_nop 0
	s_waitcnt vmcnt(0)
; __device__ __forceinline__ unsigned cvt_pk_bf16(float lo, float hi) { unsigned r; asm volatile("v_cvt_pk_bf16_f32 %0, %1, %2" : "=v"(r) : "v"(lo), "v"(hi)); return r; }
; #define MFMA16(a, b, c) __builtin_amdgcn_mfma_f32_16x16x32_bf16((a), (b), (c), 0, 0, 0)
; #define UNPK8(VV_, XX_) float XX_[8] = {bflo((VV_).x), bfhi((VV_).x), bflo((VV_).y), bfhi((VV_).y), bflo((VV_).z), bfhi((VV_).z), bflo((VV_).w), bfhi((VV_).w)}
; __device__ __forceinline__ void kvproj_task(int t, int l, const float* kvnorm, const float* kgain, const bf16_t* P, const bf16_t* WUKV, bf16_t* KB, bf16_t* VT, int fr, int fq) {
;     ...
;         for (int ks = 0; ks < 4; ++ks) { const float* gp = kvnorm + l * 128 + ks * 32 + fq * 8; const f32x4 g0 = *(const f32x4*)gp, g1 = *(const f32x4*)(gp + 4); UNPK8(raw[ks], x); u32x4 o;
;             o.x = cvt_pk_bf16(x[0] * rinv * g0[0], x[1] * rinv * g0[1]); o.y = cvt_pk_bf16(x[2] * rinv * g0[2], x[3] * rinv * g0[3]);
;             o.z = cvt_pk_bf16(x[4] * rinv * g1[0], x[5] * rinv * g1[1]); o.w = cvt_pk_bf16(x[6] * rinv * g1[2], x[7] * rinv * g1[3]);
;             bfr[tb][ks] = asfrag(o); }
;         skr[tb] = (kr[tb][0][0] * kr[tb][0][0] + kr[tb][0][1] * kr[tb][0][1]) + (kr[tb][0][2] * kr[tb][0][2] + kr[tb][0][3] * kr[tb][0][3]) + (kr[tb][1][0] * kr[tb][1][0] + kr[tb][1][1] * kr[tb][1][1]) + (kr[tb][1][2] * kr[tb][1][2] + kr[tb][1][3] * kr[tb][1][3]); }
;     const bf16_t* wk0 = WUKV + ((size_t)l * 512 + h * 128 + fr) * 128 + fq * 8;
;     bf16x8 wf[2][4];
; #pragma unroll
;     for (int ks = 0; ks < 4; ++ks) wf[0][ks] = asfrag(ld8(wk0 + ks * 32));
;     f32x4 acc[2][8];
; #pragma unroll
;     for (int cb = 0; cb < 8; ++cb) { acc[0][cb] = (f32x4){0.f, 0.f, 0.f, 0.f}; acc[1][cb] = acc[0][cb];
;         const int nrow = cb < 7 ? (cb + 1) * 16 : 0;
; #pragma unroll
;         for (int ks = 0; ks < 4; ++ks) wf[(cb + 1) & 1][ks] = asfrag(ld8(wk0 + (size_t)nrow * 128 + ks * 32));
; #pragma unroll
;         for (int ks = 0; ks < 4; ++ks) { acc[0][cb] = MFMA16(wf[cb & 1][ks], bfr[0][ks], acc[0][cb]); acc[1][cb] = MFMA16(wf[cb & 1][ks], bfr[1][ks], acc[1][cb]); } }
	v_mul_f32_e32 v6, v124, v28
	v_mul_f32_e32 v7, v125, v26
	v_cvt_pk_bf16_f32 v54, v6, v7
	v_mul_f32_e32 v6, v14, v29
	v_mul_f32_e32 v6, v126, v6
	v_mul_f32_e32 v7, v14, v27
	v_mul_f32_e32 v7, v127, v7
	v_cvt_pk_bf16_f32 v55, v6, v7
	v_mul_f32_e32 v6, v14, v24
	v_mul_f32_e32 v2, v132, v6
	v_mul_f32_e32 v6, v14, v22
	v_mul_f32_e32 v3, v133, v6
	v_cvt_pk_bf16_f32 v56, v2, v3
	v_mul_f32_e32 v2, v14, v25
	v_mul_f32_e32 v3, v14, v23
	v_mul_f32_e32 v2, v134, v2
	v_mul_f32_e32 v3, v135, v3
	v_cvt_pk_bf16_f32 v57, v2, v3
	s_nop 0
	s_nop 0
	s_nop 0
	s_nop 0
	s_waitcnt vmcnt(0)
	v_mul_f32_e32 v6, v140, v20
	v_mul_f32_e32 v20, v14, v21
	v_mul_f32_e32 v7, v141, v20
	v_cvt_pk_bf16_f32 v58, v6, v7
	v_mul_f32_e32 v6, v14, v18
	v_mul_f32_e32 v6, v142, v6
	v_mul_f32_e32 v7, v14, v19
	v_mul_f32_e32 v7, v143, v7
	v_cvt_pk_bf16_f32 v59, v6, v7
	v_mul_f32_e32 v6, v14, v70
	v_mul_f32_e32 v2, v162, v6
	v_mul_f32_e32 v6, v14, v62
	v_mul_f32_e32 v3, v163, v6
	v_cvt_pk_bf16_f32 v60, v2, v3
	v_mul_f32_e32 v2, v14, v64
	v_mul_f32_e32 v3, v14, v16
	v_mul_f32_e32 v2, v164, v2
	v_mul_f32_e32 v3, v165, v3
	v_cvt_pk_bf16_f32 v61, v2, v3
	s_nop 0
	s_nop 0
	s_nop 0
	s_nop 0
	v_mul_f32_e32 v16, v14, v71
	s_waitcnt vmcnt(1)
	v_mul_f32_e32 v0, v0, v121
	s_waitcnt vmcnt(0)
	v_mul_f32_e32 v6, v16, v156
	v_mul_f32_e32 v16, v14, v63
	v_mul_f32_e32 v7, v16, v157
	v_cvt_pk_bf16_f32 v62, v6, v7
	v_mul_f32_e32 v6, v14, v73
	v_mul_f32_e32 v6, v6, v158
	v_mul_f32_e32 v7, v14, v72
	v_mul_f32_e32 v7, v7, v159
	v_cvt_pk_bf16_f32 v63, v6, v7
	v_mul_f32_e32 v6, v14, v65
	v_mul_f32_e32 v2, v6, v112
	v_mul_f32_e32 v6, v14, v17
	v_mul_f32_e32 v3, v6, v113
	v_cvt_pk_bf16_f32 v64, v2, v3
	v_mul_f32_e32 v2, v14, v15
	v_mul_f32_e32 v2, v2, v120
	v_cvt_pk_bf16_f32 v65, v2, v0
	v_pk_mul_f32 v[2:3], v[182:183], v[182:183]
	v_add_u32_e32 v0, 0xffffc000, v171
	v_pk_fma_f32 v[192:193], v[180:181], v[180:181], v[2:3]
	flat_load_dwordx4 v[2:5], v[104:105]
	flat_load_dwordx4 v[6:9], v[104:105] offset:64
	flat_load_dwordx4 v[14:17], v[104:105] offset:128
	flat_load_dwordx4 v[18:21], v[104:105] offset:192
	flat_load_dwordx4 v[22:25], v[106:107]
	flat_load_dwordx4 v[26:29], v[106:107] offset:64
	flat_load_dwordx4 v[30:33], v[106:107] offset:128
	flat_load_dwordx4 v[74:77], v[106:107] offset:192
	s_waitcnt vmcnt(0) lgkmcnt(0)
	v_mfma_f32_16x16x32_bf16 v[66:69], v[2:5], v[34:37], 0
	v_mfma_f32_16x16x32_bf16 v[2:5], v[2:5], v[50:53], 0
	v_mfma_f32_16x16x32_bf16 v[66:69], v[6:9], v[38:41], v[66:69]
	v_mfma_f32_16x16x32_bf16 v[2:5], v[6:9], v[54:57], v[2:5]
	v_mfma_f32_16x16x32_bf16 v[6:9], v[14:17], v[42:45], v[66:69]
	v_mfma_f32_16x16x32_bf16 v[2:5], v[14:17], v[58:61], v[2:5]
	v_mfma_f32_16x16x32_bf16 v[66:69], v[18:21], v[46:49], v[6:9]
	v_mfma_f32_16x16x32_bf16 v[6:9], v[22:25], v[34:37], 0
	v_mfma_f32_16x16x32_bf16 v[22:25], v[22:25], v[50:53], 0
	s_nop 5
	v_mov_b32_e32 v177, v67
	v_mov_b32_e32 v175, v66
	v_mfma_f32_16x16x32_bf16 v[2:5], v[18:21], v[62:65], v[2:5]
	flat_load_dwordx4 v[14:17], v[114:115]
	flat_load_dwordx4 v[18:21], v[114:115] offset:64
	flat_load_dwordx4 v[78:81], v[114:115] offset:128
	flat_load_dwordx4 v[82:85], v[114:115] offset:192
	v_mfma_f32_16x16x32_bf16 v[6:9], v[26:29], v[38:41], v[6:9]
	v_mfma_f32_16x16x32_bf16 v[22:25], v[26:29], v[54:57], v[22:25]
	v_mfma_f32_16x16x32_bf16 v[6:9], v[30:33], v[42:45], v[6:9]
	v_mfma_f32_16x16x32_bf16 v[22:25], v[30:33], v[58:61], v[22:25]
	v_mfma_f32_16x16x32_bf16 v[70:73], v[74:77], v[46:49], v[6:9]
	v_mfma_f32_16x16x32_bf16 v[6:9], v[74:77], v[62:65], v[22:25]
	s_nop 5
	flat_load_dwordx4 v[22:25], v[122:123]
	flat_load_dwordx4 v[26:29], v[122:123] offset:64
	flat_load_dwordx4 v[30:33], v[122:123] offset:128
	flat_load_dwordx4 v[74:77], v[122:123] offset:192
	s_waitcnt vmcnt(0) lgkmcnt(0)
	v_mfma_f32_16x16x32_bf16 v[86:89], v[14:17], v[34:37], 0
	v_mfma_f32_16x16x32_bf16 v[14:17], v[14:17], v[50:53], 0
	v_mfma_f32_16x16x32_bf16 v[86:89], v[18:21], v[38:41], v[86:89]
	v_mfma_f32_16x16x32_bf16 v[14:17], v[18:21], v[54:57], v[14:17]
	v_mfma_f32_16x16x32_bf16 v[18:21], v[78:81], v[42:45], v[86:89]
	v_mfma_f32_16x16x32_bf16 v[86:89], v[22:25], v[34:37], 0
	v_mfma_f32_16x16x32_bf16 v[22:25], v[22:25], v[50:53], 0
	v_mfma_f32_16x16x32_bf16 v[14:17], v[78:81], v[58:61], v[14:17]
	v_mfma_f32_16x16x32_bf16 v[86:89], v[26:29], v[38:41], v[86:89]
	v_mfma_f32_16x16x32_bf16 v[22:25], v[26:29], v[54:57], v[22:25]
	v_mfma_f32_16x16x32_bf16 v[78:81], v[82:85], v[46:49], v[18:21]
	v_mfma_f32_16x16x32_bf16 v[18:21], v[82:85], v[62:65], v[14:17]
	s_nop 3
	flat_load_dwordx4 v[14:17], v[130:131]
	flat_load_dwordx4 v[82:85], v[130:131] offset:64
	flat_load_dwordx4 v[90:93], v[130:131] offset:128
	flat_load_dwordx4 v[222:225], v[130:131] offset:192
	v_mfma_f32_16x16x32_bf16 v[26:29], v[30:33], v[42:45], v[86:89]
	v_mfma_f32_16x16x32_bf16 v[22:25], v[30:33], v[58:61], v[22:25]
	v_mfma_f32_16x16x32_bf16 v[86:89], v[74:77], v[46:49], v[26:29]
	v_mfma_f32_16x16x32_bf16 v[26:29], v[74:77], v[62:65], v[22:25]
	s_nop 5
	flat_load_dwordx4 v[22:25], v[138:139]
	flat_load_dwordx4 v[30:33], v[138:139] offset:64
	flat_load_dwordx4 v[226:229], v[138:139] offset:128
	flat_load_dwordx4 v[230:233], v[138:139] offset:192
	s_waitcnt vmcnt(0) lgkmcnt(0)
; __device__ __forceinline__ unsigned cvt_pk_bf16(float lo, float hi) { unsigned r; asm volatile("v_cvt_pk_bf16_f32 %0, %1, %2" : "=v"(r) : "v"(lo), "v"(hi)); return r; }
; #define MFMA16(a, b, c) __builtin_amdgcn_mfma_f32_16x16x32_bf16((a), (b), (c), 0, 0, 0)
; __device__ __forceinline__ void kvproj_task(int t, int l, const float* kvnorm, const float* kgain, const bf16_t* P, const bf16_t* WUKV, bf16_t* KB, bf16_t* VT, int fr, int fq) {
;     ...
;     for (int cb = 0; cb < 8; ++cb) { acc[0][cb] = (f32x4){0.f, 0.f, 0.f, 0.f}; acc[1][cb] = acc[0][cb];
;         const int nrow = cb < 7 ? (cb + 1) * 16 : 0;
; #pragma unroll
;         for (int ks = 0; ks < 4; ++ks) wf[(cb + 1) & 1][ks] = asfrag(ld8(wk0 + (size_t)nrow * 128 + ks * 32));
; #pragma unroll
;         for (int ks = 0; ks < 4; ++ks) { acc[0][cb] = MFMA16(wf[cb & 1][ks], bfr[0][ks], acc[0][cb]); acc[1][cb] = MFMA16(wf[cb & 1][ks], bfr[1][ks], acc[1][cb]); } }
; #pragma unroll
;     for (int tb = 0; tb < 2; ++tb) { const int row = row0 + tb * 16, rr = isc ? row - ML : row;
;         const int b = isc ? rr >> 8 : rr >> 11, tpos = isc ? rr & 255 : rr & 2047, key = isc ? tpos : 256 + tpos;
;         float s2 = skr[tb];
; #pragma unroll
;         for (int cb = 0; cb < 4; ++cb) s2 += (acc[tb][cb][0] * acc[tb][cb][0] + acc[tb][cb][1] * acc[tb][cb][1]) + (acc[tb][cb][2] * acc[tb][cb][2] + acc[tb][cb][3] * acc[tb][cb][3]);
;         s2 += __shfl_xor(s2, 16); s2 += __shfl_xor(s2, 32);
;         const float rh = rsqrtf(s2 * (1.f / 96.f) + EPS);
;         bf16_t* kdst = KB + ((size_t)(b * 4 + h) * NKEY + key) * 96;
; #pragma unroll
;         for (int cb = 0; cb < 6; ++cb) { const f32x4 kg = *(const f32x4*)(kgain + l * 96 + cb * 16 + fq * 4); f32x4 v = (cb < 4 ? acc[tb][cb < 4 ? cb : 0] : kr[tb][cb >= 4 ? cb - 4 : 0]) * rh * kg;
;             if (cb >= 4) { const f32x4 rv = rope16(v, fq, (float)(cb == 4 ? (tpos >> 6) : (tpos & 63))); if (!isc) v = rv; }
;             u32x2 w; w.x = cvt_pk_bf16(v[0], v[1]); w.y = cvt_pk_bf16(v[2], v[3]);
;             *(u32x2*)(kdst + cb * 16 + fq * 4) = w; }
	v_mfma_f32_16x16x32_bf16 v[74:77], v[14:17], v[34:37], 0
	v_mfma_f32_16x16x32_bf16 v[14:17], v[14:17], v[50:53], 0
	v_mfma_f32_16x16x32_bf16 v[74:77], v[82:85], v[38:41], v[74:77]
	v_mfma_f32_16x16x32_bf16 v[14:17], v[82:85], v[54:57], v[14:17]
	v_mfma_f32_16x16x32_bf16 v[82:85], v[22:25], v[34:37], 0
	v_mfma_f32_16x16x32_bf16 v[22:25], v[22:25], v[50:53], 0
	v_mfma_f32_16x16x32_bf16 v[82:85], v[30:33], v[38:41], v[82:85]
	v_mfma_f32_16x16x32_bf16 v[22:25], v[30:33], v[54:57], v[22:25]
	v_mfma_f32_16x16x32_bf16 v[74:77], v[90:93], v[42:45], v[74:77]
	v_mfma_f32_16x16x32_bf16 v[14:17], v[90:93], v[58:61], v[14:17]
	v_mfma_f32_16x16x32_bf16 v[30:33], v[226:229], v[42:45], v[82:85]
	v_mfma_f32_16x16x32_bf16 v[22:25], v[226:229], v[58:61], v[22:25]
	v_mfma_f32_16x16x32_bf16 v[74:77], v[222:225], v[46:49], v[74:77]
	v_mfma_f32_16x16x32_bf16 v[14:17], v[222:225], v[62:65], v[14:17]
	flat_load_dwordx4 v[90:93], v[146:147]
	flat_load_dwordx4 v[222:225], v[146:147] offset:64
	flat_load_dwordx4 v[234:237], v[146:147] offset:128
	flat_load_dwordx4 v[238:241], v[146:147] offset:192
	v_mfma_f32_16x16x32_bf16 v[82:85], v[230:233], v[46:49], v[30:33]
	v_mfma_f32_16x16x32_bf16 v[22:25], v[230:233], v[62:65], v[22:25]
	flat_load_dwordx4 v[226:229], v[160:161]
	flat_load_dwordx4 v[230:233], v[160:161] offset:64
	flat_load_dwordx4 v[242:245], v[160:161] offset:128
	flat_load_dwordx4 v[246:249], v[160:161] offset:192
	s_waitcnt vmcnt(0) lgkmcnt(0)
	v_mfma_f32_16x16x32_bf16 v[30:33], v[90:93], v[34:37], 0
	v_mfma_f32_16x16x32_bf16 v[34:37], v[226:229], v[34:37], 0
	v_mfma_f32_16x16x32_bf16 v[90:93], v[90:93], v[50:53], 0
	v_mfma_f32_16x16x32_bf16 v[50:53], v[226:229], v[50:53], 0
	v_mfma_f32_16x16x32_bf16 v[30:33], v[222:225], v[38:41], v[30:33]
	v_mfma_f32_16x16x32_bf16 v[34:37], v[230:233], v[38:41], v[34:37]
	v_mfma_f32_16x16x32_bf16 v[38:41], v[230:233], v[54:57], v[50:53]
	v_mfma_f32_16x16x32_bf16 v[90:93], v[222:225], v[54:57], v[90:93]
	v_cndmask_b32_e32 v54, v171, v0, vcc
	v_mul_f32_e32 v0, v68, v68
	s_nop 1
	v_mul_f32_e32 v50, v69, v69
	v_mfma_f32_16x16x32_bf16 v[30:33], v[234:237], v[42:45], v[30:33]
	v_mfma_f32_16x16x32_bf16 v[34:37], v[242:245], v[42:45], v[34:37]
	v_mfma_f32_16x16x32_bf16 v[42:45], v[242:245], v[58:61], v[38:41]
	v_mfma_f32_16x16x32_bf16 v[222:225], v[234:237], v[58:61], v[90:93]
	v_mfma_f32_16x16x32_bf16 v[90:93], v[238:241], v[46:49], v[30:33]
	v_mfma_f32_16x16x32_bf16 v[38:41], v[246:249], v[46:49], v[34:37]
	v_add_f32_e64 v46, v190, v191
	v_add_f32_e64 v47, v191, v190
	v_mov_b32_e32 v47, v0
	v_mul_f32_e32 v0, v185, v185
	v_pk_fma_f32 v[48:49], v[184:185], v[184:185], v[0:1] op_sel_hi:[1,1,0]
	v_mfma_f32_16x16x32_bf16 v[34:37], v[246:249], v[62:65], v[42:45]
	v_mov_b32_e32 v49, v50
	v_pk_add_f32 v[46:47], v[46:47], v[48:49]
	v_pk_mul_f32 v[48:49], v[70:71], v[70:71]
	v_pk_mul_f32 v[44:45], v[176:177], v[176:177]
	v_mul_f32_e32 v0, v86, v86
	v_pk_fma_f32 v[44:45], v[174:175], v[174:175], v[44:45]
	v_cndmask_b32_e32 v43, v200, v201, vcc
	v_pk_add_f32 v[44:45], v[44:45], v[46:47]
	v_pk_mul_f32 v[46:47], v[72:73], v[72:73]
	v_pk_add_f32 v[44:45], v[44:45], v[44:45] op_sel:[0,1] op_sel_hi:[1,0]
	v_pk_mov_b32 v[50:51], v[48:49], v[46:47] op_sel:[1,0]
	v_mov_b32_e32 v49, v47
	v_pk_add_f32 v[46:47], v[50:51], v[48:49]
	v_mul_f32_e32 v48, v87, v87
	v_pk_add_f32 v[46:47], v[46:47], v[46:47] op_sel:[0,1] op_sel_hi:[1,0]
	v_mov_b32_e32 v45, v0
	v_mov_b32_e32 v47, v48
	v_mul_f32_e32 v0, v79, v79
	v_mul_f32_e32 v49, v88, v88
	v_pk_add_f32 v[44:45], v[44:45], v[46:47]
	v_pk_fma_f32 v[46:47], v[78:79], v[78:79], v[0:1] op_sel_hi:[1,1,0]
	v_mul_f32_e32 v0, v81, v81
	v_mul_f32_e32 v50, v89, v89
	v_mov_b32_e32 v47, v49
	v_pk_fma_f32 v[48:49], v[80:81], v[80:81], v[0:1] op_sel_hi:[1,1,0]
	v_cndmask_b32_e64 v42, 11, 8, vcc
	v_mov_b32_e32 v49, v50
	v_pk_add_f32 v[46:47], v[46:47], v[48:49]
	v_and_b32_e32 v55, v54, v43
	v_pk_add_f32 v[44:45], v[44:45], v[46:47]
	v_add_u32_e32 v52, 0x100, v55
	v_add_f32_e32 v44, v44, v45
	ds_bpermute_b32 v46, v215, v44
	v_ashrrev_i32_e32 v45, v42, v54
	v_cndmask_b32_e32 v0, v52, v55, vcc
	v_lshl_or_b32 v50, v45, 2, s22
	v_lshrrev_b32_e32 v49, 6, v55
	s_waitcnt lgkmcnt(0)
	v_add_f32_e32 v44, v44, v46
	ds_bpermute_b32 v46, v216, v44
	v_mfma_f32_16x16x32_bf16 v[30:33], v[238:241], v[62:65], v[222:225]
	v_and_b32_e32 v64, 47, v54
	v_mov_b32_e32 v175, v176
	v_ashrrev_i32_e32 v51, 31, v50
	s_waitcnt lgkmcnt(0)
	v_add_f32_e32 v44, v44, v46
	v_fmamk_f32 v44, v44, 0x3c2aaaab, v197
	v_cmp_gt_f32_e64 s[38:39], s47, v44
	v_mul_f32_e32 v46, 0x4b800000, v44
	s_nop 0
	v_cndmask_b32_e64 v44, v44, v46, s[38:39]
	v_rsq_f32_e32 v44, v44
	s_nop 0
	v_mul_f32_e32 v46, 0x45800000, v44
	v_cndmask_b32_e64 v48, v44, v46, s[38:39]
	v_mad_i64_i32 v[44:45], s[6:7], v50, s9, v[0:1]
	v_mad_u64_u32 v[52:53], s[6:7], v44, s14, v[102:103]
	v_mad_i32_i24 v53, v45, s14, v53
	global_load_dwordx4 v[44:47], v[100:101], off
	v_pk_mul_f32 v[56:57], v[66:67], v[48:49] op_sel_hi:[1,0]
	v_pk_mul_f32 v[54:55], v[68:69], v[48:49] op_sel_hi:[1,0]
	v_lshlrev_b32_e32 v0, 1, v0
	s_waitcnt vmcnt(0)
	v_pk_mul_f32 v[44:45], v[44:45], v[56:57]
	v_pk_mul_f32 v[46:47], v[46:47], v[54:55]
	v_cvt_pk_bf16_f32 v44, v44, v45
	v_pk_mul_f32 v[56:57], v[70:71], v[48:49] op_sel_hi:[1,0]
	v_cvt_pk_bf16_f32 v45, v46, v47
	flat_store_dwordx2 v[52:53], v[44:45]
	global_load_dwordx4 v[44:47], v[100:101], off offset:64
	v_pk_mul_f32 v[54:55], v[72:73], v[48:49] op_sel_hi:[1,0]
	s_waitcnt vmcnt(0)
; __device__ __forceinline__ unsigned cvt_pk_bf16(float lo, float hi) { unsigned r; asm volatile("v_cvt_pk_bf16_f32 %0, %1, %2" : "=v"(r) : "v"(lo), "v"(hi)); return r; }
; __device__ __forceinline__ bf16_t tobf(float f) { return (bf16_t)(cvt_pk_bf16(f, 0.f) & 0xffffu); }
; __device__ __forceinline__ f32x4 rope16(f32x4 v, int fq, float pos) {
;     f32x4 pr; pr[0] = __shfl_xor(v[0], 32); pr[1] = __shfl_xor(v[1], 32); pr[2] = __shfl_xor(v[2], 32); pr[3] = __shfl_xor(v[3], 32);
;     f32x4 o;
; #pragma unroll
;     for (int q = 0; q < 4; ++q) { const int f = (fq * 4 + q) & 7; const float inv = __builtin_amdgcn_exp2f(-(float)f * 1.6609640474f); float sn, cs; __sincosf(pos * inv, &sn, &cs);
;         o[q] = fq < 2 ? v[q] * cs - pr[q] * sn : pr[q] * sn + v[q] * cs; }
;     return o;
; __device__ __forceinline__ void kvproj_task(int t, int l, const float* kvnorm, const float* kgain, const bf16_t* P, const bf16_t* WUKV, bf16_t* KB, bf16_t* VT, int fr, int fq) {
;     ...
;         for (int cb = 0; cb < 6; ++cb) { const f32x4 kg = *(const f32x4*)(kgain + l * 96 + cb * 16 + fq * 4); f32x4 v = (cb < 4 ? acc[tb][cb < 4 ? cb : 0] : kr[tb][cb >= 4 ? cb - 4 : 0]) * rh * kg;
;             if (cb >= 4) { const f32x4 rv = rope16(v, fq, (float)(cb == 4 ? (tpos >> 6) : (tpos & 63))); if (!isc) v = rv; }
;             u32x2 w; w.x = cvt_pk_bf16(v[0], v[1]); w.y = cvt_pk_bf16(v[2], v[3]);
;             *(u32x2*)(kdst + cb * 16 + fq * 4) = w; }
; #pragma unroll
;         for (int cb = 4; cb < 8; ++cb)
; #pragma unroll
;             for (int q = 0; q < 4; ++q) VT[((size_t)(b * 4 + h) * 64 + (cb - 4) * 16 + fq * 4 + q) * NKEY + key] = tobf(acc[tb][cb][q]); }
	v_pk_mul_f32 v[44:45], v[44:45], v[56:57]
	v_pk_mul_f32 v[46:47], v[46:47], v[54:55]
	v_cvt_pk_bf16_f32 v44, v44, v45
	v_pk_mul_f32 v[56:57], v[78:79], v[48:49] op_sel_hi:[1,0]
	v_cvt_pk_bf16_f32 v45, v46, v47
	flat_store_dwordx2 v[52:53], v[44:45] offset:32
	global_load_dwordx4 v[44:47], v[100:101], off offset:128
	v_pk_mul_f32 v[54:55], v[80:81], v[48:49] op_sel_hi:[1,0]
	s_waitcnt vmcnt(0)
	v_pk_mul_f32 v[44:45], v[44:45], v[56:57]
	v_pk_mul_f32 v[46:47], v[46:47], v[54:55]
	v_cvt_pk_bf16_f32 v44, v44, v45
	v_pk_mul_f32 v[56:57], v[86:87], v[48:49] op_sel_hi:[1,0]
	v_cvt_pk_bf16_f32 v45, v46, v47
	flat_store_dwordx2 v[52:53], v[44:45] offset:64
	global_load_dwordx4 v[44:47], v[100:101], off offset:192
	v_pk_mul_f32 v[54:55], v[88:89], v[48:49] op_sel_hi:[1,0]
	s_waitcnt vmcnt(0)
	v_pk_mul_f32 v[44:45], v[56:57], v[44:45]
	v_pk_mul_f32 v[46:47], v[54:55], v[46:47]
	v_cvt_pk_bf16_f32 v44, v44, v45
	v_mov_b32_e32 v54, v186
	v_cvt_pk_bf16_f32 v45, v46, v47
	flat_store_dwordx2 v[52:53], v[44:45] offset:96
	global_load_dwordx4 v[44:47], v[100:101], off offset:256
	v_mov_b32_e32 v55, v188
	v_mov_b32_e32 v188, v187
	v_pk_mul_f32 v[54:55], v[48:49], v[54:55] op_sel_hi:[0,1]
	v_pk_mul_f32 v[56:57], v[48:49], v[188:189] op_sel_hi:[0,1]
	v_cvt_f32_ubyte0_e32 v49, v49
	v_mul_f32_e32 v58, v217, v49
	v_mul_f32_e32 v59, 0.15915494, v58
	v_cos_f32_e32 v58, v59
	v_sin_f32_e32 v60, v59
	v_mul_f32_e32 v59, v218, v49
	v_mul_f32_e32 v61, 0.15915494, v59
	v_cos_f32_e32 v59, v61
	v_sin_f32_e32 v61, v61
	s_waitcnt vmcnt(0)
	v_pk_mul_f32 v[44:45], v[54:55], v[44:45]
	ds_bpermute_b32 v54, v216, v44
	ds_bpermute_b32 v55, v216, v45
	v_pk_mul_f32 v[46:47], v[56:57], v[46:47]
	ds_bpermute_b32 v56, v216, v46
	ds_bpermute_b32 v57, v216, v47
	s_waitcnt lgkmcnt(0)
	v_pk_mul_f32 v[54:55], v[60:61], v[54:55]
	v_mul_f32_e32 v60, v219, v49
	v_mul_f32_e32 v49, v220, v49
	v_mul_f32_e32 v61, 0.15915494, v60
	v_mul_f32_e32 v49, 0.15915494, v49
	v_sin_f32_e32 v62, v61
	v_sin_f32_e32 v63, v49
	v_cos_f32_e32 v60, v61
	v_cos_f32_e32 v61, v49
	v_cndmask_b32_e64 v55, v55, -v55, s[36:37]
	v_pk_mul_f32 v[56:57], v[62:63], v[56:57]
	v_cndmask_b32_e64 v54, v54, -v54, s[36:37]
	v_cndmask_b32_e64 v57, v57, -v57, s[36:37]
	v_cndmask_b32_e64 v56, v56, -v56, s[36:37]
	v_pk_fma_f32 v[54:55], v[58:59], v[44:45], v[54:55]
	v_pk_fma_f32 v[56:57], v[60:61], v[46:47], v[56:57]
	v_cndmask_b32_e32 v44, v54, v44, vcc
	v_cndmask_b32_e32 v45, v55, v45, vcc
	v_cndmask_b32_e32 v46, v56, v46, vcc
	v_cndmask_b32_e32 v47, v57, v47, vcc
	v_cvt_pk_bf16_f32 v44, v44, v45
	v_cvt_pk_bf16_f32 v45, v46, v47
	flat_store_dwordx2 v[52:53], v[44:45] offset:128
	global_load_dwordx4 v[44:47], v[100:101], off offset:320
	v_cvt_f32_ubyte0_e32 v61, v64
	v_mul_f32_e32 v56, v217, v61
	v_pk_mul_f32 v[54:55], v[48:49], v[184:185] op_sel_hi:[0,1]
	v_mul_f32_e32 v57, 0.15915494, v56
	v_pk_mul_f32 v[48:49], v[48:49], v[174:175] op_sel_hi:[0,1]
	v_cos_f32_e32 v56, v57
	v_sin_f32_e32 v58, v57
	v_mul_f32_e32 v57, v218, v61
	v_mul_f32_e32 v59, 0.15915494, v57
	v_cos_f32_e32 v57, v59
	v_sin_f32_e32 v59, v59
	s_waitcnt vmcnt(0)
	v_pk_mul_f32 v[44:45], v[54:55], v[44:45]
	v_pk_mul_f32 v[46:47], v[48:49], v[46:47]
	ds_bpermute_b32 v48, v216, v44
	ds_bpermute_b32 v49, v216, v45
	ds_bpermute_b32 v54, v216, v46
	ds_bpermute_b32 v55, v216, v47
	s_waitcnt lgkmcnt(0)
	v_pk_mul_f32 v[48:49], v[58:59], v[48:49]
	v_mul_f32_e32 v58, v219, v61
	v_mul_f32_e32 v59, 0.15915494, v58
	v_cos_f32_e32 v58, v59
	v_sin_f32_e32 v60, v59
	v_mul_f32_e32 v59, v220, v61
	v_mul_f32_e32 v61, 0.15915494, v59
	v_cos_f32_e32 v59, v61
	v_sin_f32_e32 v61, v61
	v_cndmask_b32_e64 v49, v49, -v49, s[36:37]
	v_cndmask_b32_e64 v48, v48, -v48, s[36:37]
	v_pk_fma_f32 v[48:49], v[56:57], v[44:45], v[48:49]
	v_pk_mul_f32 v[54:55], v[60:61], v[54:55]
	v_cndmask_b32_e32 v44, v48, v44, vcc
	v_cndmask_b32_e64 v55, v55, -v55, s[36:37]
	v_cndmask_b32_e64 v54, v54, -v54, s[36:37]
	v_pk_fma_f32 v[54:55], v[58:59], v[46:47], v[54:55]
	v_cndmask_b32_e32 v45, v49, v45, vcc
	v_cndmask_b32_e32 v46, v54, v46, vcc
	v_cndmask_b32_e32 v47, v55, v47, vcc
	v_cvt_pk_bf16_f32 v44, v44, v45
	v_cvt_pk_bf16_f32 v45, v46, v47
	v_lshlrev_b64 v[46:47], 6, v[50:51]
	flat_store_dwordx2 v[52:53], v[44:45] offset:160
	v_lshl_add_u64 v[44:45], s[40:41], 0, v[0:1]
	v_or_b32_e32 v0, v46, v96
	v_mad_u64_u32 v[44:45], s[6:7], v0, s88, v[44:45]
	v_cvt_pk_bf16_f32 v46, v74, v1
	v_mad_i32_i24 v45, v47, s88, v45
	flat_store_short v[44:45], v46
	v_add_co_u32_e64 v46, s[38:39], s19, v44
	v_cvt_pk_bf16_f32 v0, v75, v1
	s_nop 1
	v_addc_co_u32_e64 v47, s[38:39], 0, v45, s[38:39]
	flat_store_short v[46:47], v0 offset:512
	v_add_co_u32_e64 v46, s[38:39], s33, v44
	v_cvt_pk_bf16_f32 v0, v76, v1
	s_nop 1
	v_addc_co_u32_e64 v47, s[38:39], 0, v45, s[38:39]
	flat_store_short v[46:47], v0 offset:1024
	v_add_co_u32_e64 v46, s[38:39], s23, v44
	v_cvt_pk_bf16_f32 v0, v77, v1
	s_nop 1
	v_addc_co_u32_e64 v47, s[38:39], 0, v45, s[38:39]
	flat_store_short v[46:47], v0 offset:1536
	v_add_co_u32_e64 v46, s[38:39], s15, v44
	v_cvt_pk_bf16_f32 v0, v82, v1
	s_nop 1
	v_addc_co_u32_e64 v47, s[38:39], 0, v45, s[38:39]
	flat_store_short v[46:47], v0
	v_add_co_u32_e64 v46, s[38:39], s24, v44
	v_cvt_pk_bf16_f32 v0, v83, v1
	s_nop 1
	v_addc_co_u32_e64 v47, s[38:39], 0, v45, s[38:39]
	flat_store_short v[46:47], v0 offset:512
	v_add_co_u32_e64 v46, s[38:39], s18, v44
	v_cvt_pk_bf16_f32 v0, v84, v1
	s_nop 1
	v_addc_co_u32_e64 v47, s[38:39], 0, v45, s[38:39]
	flat_store_short v[46:47], v0 offset:1024
	v_add_co_u32_e64 v46, s[38:39], s25, v44
	v_cvt_pk_bf16_f32 v0, v85, v1
	s_nop 1
	v_addc_co_u32_e64 v47, s[38:39], 0, v45, s[38:39]
; __device__ __forceinline__ unsigned cvt_pk_bf16(float lo, float hi) { unsigned r; asm volatile("v_cvt_pk_bf16_f32 %0, %1, %2" : "=v"(r) : "v"(lo), "v"(hi)); return r; }
; __device__ __forceinline__ bf16_t tobf(float f) { return (bf16_t)(cvt_pk_bf16(f, 0.f) & 0xffffu); }
; __device__ __forceinline__ void kvproj_task(int t, int l, const float* kvnorm, const float* kgain, const bf16_t* P, const bf16_t* WUKV, bf16_t* KB, bf16_t* VT, int fr, int fq) {
;     ...
;     for (int tb = 0; tb < 2; ++tb) { const int row = row0 + tb * 16, rr = isc ? row - ML : row;
;         const int b = isc ? rr >> 8 : rr >> 11, tpos = isc ? rr & 255 : rr & 2047, key = isc ? tpos : 256 + tpos;
;         float s2 = skr[tb];
; #pragma unroll
;         for (int cb = 0; cb < 4; ++cb) s2 += (acc[tb][cb][0] * acc[tb][cb][0] + acc[tb][cb][1] * acc[tb][cb][1]) + (acc[tb][cb][2] * acc[tb][cb][2] + acc[tb][cb][3] * acc[tb][cb][3]);
;         s2 += __shfl_xor(s2, 16); s2 += __shfl_xor(s2, 32);
;         const float rh = rsqrtf(s2 * (1.f / 96.f) + EPS);
;         bf16_t* kdst = KB + ((size_t)(b * 4 + h) * NKEY + key) * 96;
; #pragma unroll
;         for (int cb = 0; cb < 6; ++cb) { const f32x4 kg = *(const f32x4*)(kgain + l * 96 + cb * 16 + fq * 4); f32x4 v = (cb < 4 ? acc[tb][cb < 4 ? cb : 0] : kr[tb][cb >= 4 ? cb - 4 : 0]) * rh * kg;
;             if (cb >= 4) { const f32x4 rv = rope16(v, fq, (float)(cb == 4 ? (tpos >> 6) : (tpos & 63))); if (!isc) v = rv; }
;             u32x2 w; w.x = cvt_pk_bf16(v[0], v[1]); w.y = cvt_pk_bf16(v[2], v[3]);
;             *(u32x2*)(kdst + cb * 16 + fq * 4) = w; }
; #pragma unroll
;         for (int cb = 4; cb < 8; ++cb)
; #pragma unroll
;             for (int q = 0; q < 4; ++q) VT[((size_t)(b * 4 + h) * 64 + (cb - 4) * 16 + fq * 4 + q) * NKEY + key] = tobf(acc[tb][cb][q]); }
	flat_store_short v[46:47], v0 offset:1536
	v_add_co_u32_e64 v46, s[38:39], s26, v44
	v_cvt_pk_bf16_f32 v0, v90, v1
	s_nop 1
	v_addc_co_u32_e64 v47, s[38:39], 0, v45, s[38:39]
	flat_store_short v[46:47], v0
	v_add_co_u32_e64 v46, s[38:39], s27, v44
	v_cvt_pk_bf16_f32 v0, v91, v1
	s_nop 1
	v_addc_co_u32_e64 v47, s[38:39], 0, v45, s[38:39]
	flat_store_short v[46:47], v0 offset:512
	v_add_co_u32_e64 v46, s[38:39], s44, v44
	v_cvt_pk_bf16_f32 v0, v92, v1
	s_nop 1
	v_addc_co_u32_e64 v47, s[38:39], 0, v45, s[38:39]
	flat_store_short v[46:47], v0 offset:1024
	v_add_co_u32_e64 v46, s[38:39], s45, v44
	v_cvt_pk_bf16_f32 v0, v93, v1
	s_nop 1
	v_addc_co_u32_e64 v47, s[38:39], 0, v45, s[38:39]
	flat_store_short v[46:47], v0 offset:1536
	v_add_co_u32_e64 v46, s[38:39], s46, v44
	v_cvt_pk_bf16_f32 v0, v38, v1
	s_nop 1
	v_addc_co_u32_e64 v47, s[38:39], 0, v45, s[38:39]
	v_add_co_u32_e64 v38, s[38:39], s48, v44
	flat_store_short v[46:47], v0
	v_cvt_pk_bf16_f32 v0, v39, v1
	s_nop 0
	v_addc_co_u32_e64 v39, s[38:39], 0, v45, s[38:39]
	flat_store_short v[38:39], v0 offset:512
	v_add_co_u32_e64 v38, s[38:39], s51, v44
	v_cvt_pk_bf16_f32 v0, v40, v1
	v_pk_add_f32 v[46:47], v[192:193], v[192:193] op_sel:[0,1] op_sel_hi:[1,0]
	s_nop 0
	v_addc_co_u32_e64 v39, s[38:39], 0, v45, s[38:39]
	flat_store_short v[38:39], v0 offset:1024
	v_add_co_u32_e64 v38, s[38:39], s52, v44
	v_cvt_pk_bf16_f32 v0, v41, v1
	s_nop 1
	v_addc_co_u32_e64 v39, s[38:39], 0, v45, s[38:39]
	flat_store_short v[38:39], v0 offset:1536
	v_add_u32_e32 v0, 0xffffc010, v171
	v_cndmask_b32_e32 v39, v173, v0, vcc
	v_mul_f32_e32 v0, v4, v4
	v_mov_b32_e32 v47, v0
	v_mul_f32_e32 v0, v179, v179
	v_and_b32_e32 v44, v39, v43
	v_mul_f32_e32 v43, v5, v5
	v_mov_b32_e32 v173, v3
	v_pk_fma_f32 v[48:49], v[178:179], v[178:179], v[0:1] op_sel_hi:[1,1,0]
	v_mov_b32_e32 v171, v2
	v_pk_mul_f32 v[40:41], v[172:173], v[172:173]
	v_mov_b32_e32 v49, v43
	v_pk_fma_f32 v[40:41], v[170:171], v[170:171], v[40:41]
	v_pk_add_f32 v[46:47], v[46:47], v[48:49]
	v_pk_mul_f32 v[48:49], v[6:7], v[6:7]
	v_pk_add_f32 v[40:41], v[40:41], v[46:47]
	v_pk_mul_f32 v[46:47], v[8:9], v[8:9]
	v_mul_f32_e32 v0, v26, v26
	v_pk_mov_b32 v[50:51], v[48:49], v[46:47] op_sel:[1,0]
	v_mov_b32_e32 v49, v47
	v_pk_add_f32 v[46:47], v[50:51], v[48:49]
	v_mul_f32_e32 v43, v27, v27
	v_pk_add_f32 v[40:41], v[40:41], v[40:41] op_sel:[0,1] op_sel_hi:[1,0]
	v_pk_add_f32 v[46:47], v[46:47], v[46:47] op_sel:[0,1] op_sel_hi:[1,0]
	v_mov_b32_e32 v41, v0
	v_mov_b32_e32 v47, v43
	v_mul_f32_e32 v0, v19, v19
	v_pk_add_f32 v[40:41], v[40:41], v[46:47]
	v_pk_fma_f32 v[46:47], v[18:19], v[18:19], v[0:1] op_sel_hi:[1,1,0]
	v_mul_f32_e32 v0, v21, v21
	v_mul_f32_e32 v45, v28, v28
	v_mul_f32_e32 v50, v29, v29
	v_pk_fma_f32 v[48:49], v[20:21], v[20:21], v[0:1] op_sel_hi:[1,1,0]
	v_mov_b32_e32 v47, v45
	v_mov_b32_e32 v49, v50
	v_pk_add_f32 v[46:47], v[46:47], v[48:49]
	v_add_u32_e32 v38, 0x100, v44
	v_pk_add_f32 v[40:41], v[40:41], v[46:47]
	v_cndmask_b32_e32 v0, v38, v44, vcc
	v_add_f32_e32 v40, v40, v41
	ds_bpermute_b32 v38, v215, v40
	v_ashrrev_i32_e32 v41, v42, v39
	v_lshrrev_b32_e32 v44, 6, v44
	v_mov_b32_e32 v171, v172
	s_waitcnt lgkmcnt(0)
	v_add_f32_e32 v38, v40, v38
	ds_bpermute_b32 v40, v216, v38
	s_waitcnt lgkmcnt(0)
	v_add_f32_e32 v38, v38, v40
	v_fmamk_f32 v38, v38, 0x3c2aaaab, v197
	v_cmp_gt_f32_e64 s[38:39], s47, v38
	v_mul_f32_e32 v40, 0x4b800000, v38
	s_nop 0
	v_cndmask_b32_e64 v38, v38, v40, s[38:39]
	v_rsq_f32_e32 v38, v38
	s_nop 0
	v_mul_f32_e32 v40, 0x45800000, v38
	v_cndmask_b32_e64 v38, v38, v40, s[38:39]
	v_lshl_or_b32 v40, v41, 2, s22
	v_mad_i64_i32 v[46:47], s[6:7], v40, s9, v[0:1]
	v_mad_u64_u32 v[42:43], s[6:7], v46, s14, v[102:103]
	v_mad_i32_i24 v43, v47, s14, v43
	global_load_dwordx4 v[46:49], v[100:101], off
	v_pk_mul_f32 v[2:3], v[2:3], v[38:39] op_sel_hi:[1,0]
	v_pk_mul_f32 v[4:5], v[4:5], v[38:39] op_sel_hi:[1,0]
	v_pk_mul_f32 v[6:7], v[6:7], v[38:39] op_sel_hi:[1,0]
	v_pk_mul_f32 v[8:9], v[8:9], v[38:39] op_sel_hi:[1,0]
	v_ashrrev_i32_e32 v41, 31, v40
	v_lshlrev_b32_e32 v0, 1, v0
	s_waitcnt vmcnt(0)
	v_pk_mul_f32 v[2:3], v[46:47], v[2:3]
	v_pk_mul_f32 v[4:5], v[48:49], v[4:5]
	v_cvt_pk_bf16_f32 v2, v2, v3
	s_nop 0
	v_cvt_pk_bf16_f32 v3, v4, v5
	flat_store_dwordx2 v[42:43], v[2:3]
	global_load_dwordx4 v[2:5], v[100:101], off offset:64
	s_waitcnt vmcnt(0)
	v_pk_mul_f32 v[2:3], v[2:3], v[6:7]
	v_pk_mul_f32 v[4:5], v[4:5], v[8:9]
	v_cvt_pk_bf16_f32 v2, v2, v3
	v_pk_mul_f32 v[8:9], v[18:19], v[38:39] op_sel_hi:[1,0]
	v_cvt_pk_bf16_f32 v3, v4, v5
	flat_store_dwordx2 v[42:43], v[2:3] offset:32
	global_load_dwordx4 v[2:5], v[100:101], off offset:128
	v_pk_mul_f32 v[6:7], v[20:21], v[38:39] op_sel_hi:[1,0]
	s_waitcnt vmcnt(0)
	v_pk_mul_f32 v[2:3], v[2:3], v[8:9]
	v_pk_mul_f32 v[4:5], v[4:5], v[6:7]
	v_cvt_pk_bf16_f32 v2, v2, v3
	v_pk_mul_f32 v[8:9], v[26:27], v[38:39] op_sel_hi:[1,0]
	v_cvt_pk_bf16_f32 v3, v4, v5
	flat_store_dwordx2 v[42:43], v[2:3] offset:64
	global_load_dwordx4 v[2:5], v[100:101], off offset:192
	v_pk_mul_f32 v[6:7], v[28:29], v[38:39] op_sel_hi:[1,0]
	v_cvt_f32_ubyte0_e32 v27, v44
	v_mul_f32_e32 v18, v217, v27
	v_mul_f32_e32 v19, 0.15915494, v18
	v_cos_f32_e32 v18, v19
	v_sin_f32_e32 v20, v19
	v_mul_f32_e32 v19, v218, v27
	v_mul_f32_e32 v21, 0.15915494, v19
	v_cos_f32_e32 v19, v21
	v_sin_f32_e32 v21, v21
	s_waitcnt vmcnt(0)
; __device__ __forceinline__ unsigned cvt_pk_bf16(float lo, float hi) { unsigned r; asm volatile("v_cvt_pk_bf16_f32 %0, %1, %2" : "=v"(r) : "v"(lo), "v"(hi)); return r; }
; __device__ __forceinline__ bf16_t tobf(float f) { return (bf16_t)(cvt_pk_bf16(f, 0.f) & 0xffffu); }
; __device__ __forceinline__ f32x4 rope16(f32x4 v, int fq, float pos) {
;     f32x4 pr; pr[0] = __shfl_xor(v[0], 32); pr[1] = __shfl_xor(v[1], 32); pr[2] = __shfl_xor(v[2], 32); pr[3] = __shfl_xor(v[3], 32);
;     f32x4 o;
; #pragma unroll
;     for (int q = 0; q < 4; ++q) { const int f = (fq * 4 + q) & 7; const float inv = __builtin_amdgcn_exp2f(-(float)f * 1.6609640474f); float sn, cs; __sincosf(pos * inv, &sn, &cs);
;         o[q] = fq < 2 ? v[q] * cs - pr[q] * sn : pr[q] * sn + v[q] * cs; }
;     return o;
; __device__ __forceinline__ void kvproj_task(int t, int l, const float* kvnorm, const float* kgain, const bf16_t* P, const bf16_t* WUKV, bf16_t* KB, bf16_t* VT, int fr, int fq) {
;     ...
;         for (int cb = 0; cb < 6; ++cb) { const f32x4 kg = *(const f32x4*)(kgain + l * 96 + cb * 16 + fq * 4); f32x4 v = (cb < 4 ? acc[tb][cb < 4 ? cb : 0] : kr[tb][cb >= 4 ? cb - 4 : 0]) * rh * kg;
;             if (cb >= 4) { const f32x4 rv = rope16(v, fq, (float)(cb == 4 ? (tpos >> 6) : (tpos & 63))); if (!isc) v = rv; }
;             u32x2 w; w.x = cvt_pk_bf16(v[0], v[1]); w.y = cvt_pk_bf16(v[2], v[3]);
;             *(u32x2*)(kdst + cb * 16 + fq * 4) = w; }
; #pragma unroll
;         for (int cb = 4; cb < 8; ++cb)
; #pragma unroll
;             for (int q = 0; q < 4; ++q) VT[((size_t)(b * 4 + h) * 64 + (cb - 4) * 16 + fq * 4 + q) * NKEY + key] = tobf(acc[tb][cb][q]); }
	v_pk_mul_f32 v[2:3], v[8:9], v[2:3]
	v_pk_mul_f32 v[4:5], v[6:7], v[4:5]
	v_cvt_pk_bf16_f32 v2, v2, v3
	v_mov_b32_e32 v6, v180
	v_cvt_pk_bf16_f32 v3, v4, v5
	flat_store_dwordx2 v[42:43], v[2:3] offset:96
	global_load_dwordx4 v[2:5], v[100:101], off offset:256
	v_mov_b32_e32 v7, v182
	v_pk_mul_f32 v[6:7], v[38:39], v[6:7] op_sel_hi:[0,1]
	v_mov_b32_e32 v182, v181
	v_pk_mul_f32 v[8:9], v[38:39], v[182:183] op_sel_hi:[0,1]
	s_waitcnt vmcnt(0)
	v_pk_mul_f32 v[2:3], v[6:7], v[2:3]
	ds_bpermute_b32 v6, v216, v2
	ds_bpermute_b32 v7, v216, v3
	v_pk_mul_f32 v[4:5], v[8:9], v[4:5]
	ds_bpermute_b32 v8, v216, v4
	ds_bpermute_b32 v9, v216, v5
	s_waitcnt lgkmcnt(0)
	v_pk_mul_f32 v[6:7], v[20:21], v[6:7]
	v_mul_f32_e32 v20, v219, v27
	v_mul_f32_e32 v21, 0.15915494, v20
	v_cos_f32_e32 v20, v21
	v_sin_f32_e32 v26, v21
	v_mul_f32_e32 v21, v220, v27
	v_mul_f32_e32 v27, 0.15915494, v21
	v_cos_f32_e32 v21, v27
	v_sin_f32_e32 v27, v27
	v_cndmask_b32_e64 v7, v7, -v7, s[36:37]
	v_cndmask_b32_e64 v6, v6, -v6, s[36:37]
	v_pk_fma_f32 v[6:7], v[18:19], v[2:3], v[6:7]
	v_pk_mul_f32 v[8:9], v[26:27], v[8:9]
	v_cndmask_b32_e32 v2, v6, v2, vcc
	v_cndmask_b32_e64 v9, v9, -v9, s[36:37]
	v_cndmask_b32_e64 v8, v8, -v8, s[36:37]
	v_pk_fma_f32 v[8:9], v[20:21], v[4:5], v[8:9]
	v_cndmask_b32_e32 v3, v7, v3, vcc
	v_cndmask_b32_e32 v4, v8, v4, vcc
	v_cndmask_b32_e32 v5, v9, v5, vcc
	v_cvt_pk_bf16_f32 v2, v2, v3
	v_cvt_pk_bf16_f32 v3, v4, v5
	flat_store_dwordx2 v[42:43], v[2:3] offset:128
	global_load_dwordx4 v[2:5], v[100:101], off offset:320
	v_and_b32_e32 v18, 63, v39
	v_cvt_f32_ubyte0_e32 v27, v18
	v_mul_f32_e32 v18, v217, v27
	v_pk_mul_f32 v[6:7], v[38:39], v[178:179] op_sel_hi:[0,1]
	v_mul_f32_e32 v19, 0.15915494, v18
	v_cos_f32_e32 v18, v19
	v_sin_f32_e32 v20, v19
	v_mul_f32_e32 v19, v218, v27
	v_mul_f32_e32 v21, 0.15915494, v19
	v_cos_f32_e32 v19, v21
	v_sin_f32_e32 v21, v21
	v_pk_mul_f32 v[8:9], v[38:39], v[170:171] op_sel_hi:[0,1]
	s_waitcnt vmcnt(0)
	v_pk_mul_f32 v[2:3], v[6:7], v[2:3]
	ds_bpermute_b32 v6, v216, v2
	ds_bpermute_b32 v7, v216, v3
	v_pk_mul_f32 v[4:5], v[8:9], v[4:5]
	ds_bpermute_b32 v8, v216, v4
	ds_bpermute_b32 v9, v216, v5
	s_waitcnt lgkmcnt(0)
	v_pk_mul_f32 v[6:7], v[20:21], v[6:7]
	v_mul_f32_e32 v20, v219, v27
	v_mul_f32_e32 v21, 0.15915494, v20
	v_cos_f32_e32 v20, v21
	v_sin_f32_e32 v26, v21
	v_mul_f32_e32 v21, v220, v27
	v_mul_f32_e32 v27, 0.15915494, v21
	v_cos_f32_e32 v21, v27
	v_sin_f32_e32 v27, v27
	v_cndmask_b32_e64 v7, v7, -v7, s[36:37]
	v_cndmask_b32_e64 v6, v6, -v6, s[36:37]
	v_pk_fma_f32 v[6:7], v[18:19], v[2:3], v[6:7]
	v_pk_mul_f32 v[8:9], v[26:27], v[8:9]
	v_cndmask_b32_e32 v2, v6, v2, vcc
	v_cndmask_b32_e64 v9, v9, -v9, s[36:37]
	v_cndmask_b32_e64 v8, v8, -v8, s[36:37]
	v_pk_fma_f32 v[8:9], v[20:21], v[4:5], v[8:9]
	v_cndmask_b32_e32 v3, v7, v3, vcc
	v_cndmask_b32_e32 v4, v8, v4, vcc
	v_cndmask_b32_e32 v5, v9, v5, vcc
	v_cvt_pk_bf16_f32 v2, v2, v3
	v_cvt_pk_bf16_f32 v3, v4, v5
	v_lshlrev_b64 v[4:5], 6, v[40:41]
	flat_store_dwordx2 v[42:43], v[2:3] offset:160
	v_lshl_add_u64 v[2:3], s[40:41], 0, v[0:1]
	v_or_b32_e32 v0, v4, v96
	v_mad_u64_u32 v[2:3], s[6:7], v0, s88, v[2:3]
	v_cvt_pk_bf16_f32 v4, v14, v1
	v_mad_i32_i24 v3, v5, s88, v3
	flat_store_short v[2:3], v4
	v_add_co_u32_e32 v4, vcc, s19, v2
	v_cvt_pk_bf16_f32 v0, v15, v1
	s_nop 1
	v_addc_co_u32_e32 v5, vcc, 0, v3, vcc
	flat_store_short v[4:5], v0 offset:512
	v_add_co_u32_e32 v4, vcc, s33, v2
	v_cvt_pk_bf16_f32 v0, v16, v1
	s_nop 1
	v_addc_co_u32_e32 v5, vcc, 0, v3, vcc
	flat_store_short v[4:5], v0 offset:1024
	v_add_co_u32_e32 v4, vcc, s23, v2
	v_cvt_pk_bf16_f32 v0, v17, v1
	s_nop 1
	v_addc_co_u32_e32 v5, vcc, 0, v3, vcc
	flat_store_short v[4:5], v0 offset:1536
	v_add_co_u32_e32 v4, vcc, s15, v2
	v_cvt_pk_bf16_f32 v0, v22, v1
	s_nop 1
	v_addc_co_u32_e32 v5, vcc, 0, v3, vcc
	flat_store_short v[4:5], v0
	v_add_co_u32_e32 v4, vcc, s24, v2
	v_cvt_pk_bf16_f32 v0, v23, v1
	s_nop 1
	v_addc_co_u32_e32 v5, vcc, 0, v3, vcc
	flat_store_short v[4:5], v0 offset:512
	v_add_co_u32_e32 v4, vcc, s18, v2
	v_cvt_pk_bf16_f32 v0, v24, v1
	s_nop 1
	v_addc_co_u32_e32 v5, vcc, 0, v3, vcc
	flat_store_short v[4:5], v0 offset:1024
	v_add_co_u32_e32 v4, vcc, s25, v2
	v_cvt_pk_bf16_f32 v0, v25, v1
	s_nop 1
	v_addc_co_u32_e32 v5, vcc, 0, v3, vcc
	flat_store_short v[4:5], v0 offset:1536
	v_add_co_u32_e32 v4, vcc, s26, v2
	v_cvt_pk_bf16_f32 v0, v30, v1
	s_nop 1
	v_addc_co_u32_e32 v5, vcc, 0, v3, vcc
	flat_store_short v[4:5], v0
	v_add_co_u32_e32 v4, vcc, s27, v2
	v_cvt_pk_bf16_f32 v0, v31, v1
	s_nop 1
	v_addc_co_u32_e32 v5, vcc, 0, v3, vcc
	flat_store_short v[4:5], v0 offset:512
	v_add_co_u32_e32 v4, vcc, s44, v2
	v_cvt_pk_bf16_f32 v0, v32, v1
	s_nop 1
	v_addc_co_u32_e32 v5, vcc, 0, v3, vcc
	flat_store_short v[4:5], v0 offset:1024
	v_add_co_u32_e32 v4, vcc, s45, v2
	v_cvt_pk_bf16_f32 v0, v33, v1
	s_nop 1
	v_addc_co_u32_e32 v5, vcc, 0, v3, vcc
	flat_store_short v[4:5], v0 offset:1536
	v_add_co_u32_e32 v4, vcc, s46, v2
	v_cvt_pk_bf16_f32 v0, v34, v1
	s_nop 1
	v_addc_co_u32_e32 v5, vcc, 0, v3, vcc
	flat_store_short v[4:5], v0
	v_add_co_u32_e32 v4, vcc, s48, v2
	v_cvt_pk_bf16_f32 v0, v35, v1
	s_nop 1
	v_addc_co_u32_e32 v5, vcc, 0, v3, vcc
	flat_store_short v[4:5], v0 offset:512
	v_add_co_u32_e32 v4, vcc, 0x38000, v2
	v_cvt_pk_bf16_f32 v0, v36, v1
	s_nop 1
	v_addc_co_u32_e32 v5, vcc, 0, v3, vcc
	v_add_co_u32_e32 v2, vcc, 0x39000, v2
	flat_store_short v[4:5], v0 offset:1024
	s_nop 0
	v_addc_co_u32_e32 v3, vcc, 0, v3, vcc
	v_cvt_pk_bf16_f32 v0, v37, v1
	flat_store_short v[2:3], v0 offset:1536
	s_cbranch_scc0 .LBB0_422

; __device__ __forceinline__ unsigned cvt_pk_bf16(float lo, float hi) { unsigned r; asm volatile("v_cvt_pk_bf16_f32 %0, %1, %2" : "=v"(r) : "v"(lo), "v"(hi)); return r; }
; __device__ __forceinline__ float bflo(unsigned w) { return __uint_as_float(w << 16); }
; __device__ __forceinline__ float bfhi(unsigned w) { return __uint_as_float(w & 0xffff0000u); }
; __device__ __forceinline__ void kvproj_task(int t, int l, const float* kvnorm, const float* kgain, const bf16_t* P, const bf16_t* WUKV, bf16_t* KB, bf16_t* VT, int fr, int fq) {
;     const int h = t & 3, row0 = (t >> 2) * 32 + fr; const bool isc = row0 >= ML;
;     bf16x8 bfr[2][4]; f32x4 kr[2][2]; float skr[2];
; #pragma unroll
;     for (int tb = 0; tb < 2; ++tb) { const int row = row0 + tb * 16; float ss = 0.f; u32x4 raw[4];
; #pragma unroll
;         for (int ks = 0; ks < 4; ++ks) { raw[ks] = ld8(P + (size_t)row * INP + ks * 32 + fq * 8); UNPK8(raw[ks], x);
;             ss += (x[0] * x[0] + x[1] * x[1]) + (x[2] * x[2] + x[3] * x[3]) + (x[4] * x[4] + x[5] * x[5]) + (x[6] * x[6] + x[7] * x[7]); }
; #pragma unroll
;         for (int cbr = 0; cbr < 2; ++cbr) { const u32x2 w = ld4(P + (size_t)row * INP + OFF_KROPE + cbr * 16 + fq * 4); kr[tb][cbr] = (f32x4){bflo(w.x), bfhi(w.x), bflo(w.y), bfhi(w.y)}; }
;         ss += __shfl_xor(ss, 16); ss += __shfl_xor(ss, 32);
;         const float rinv = rsqrtf(ss * (1.f / 128.f) + EPS);
; #pragma unroll
;         for (int ks = 0; ks < 4; ++ks) { const float* gp = kvnorm + l * 128 + ks * 32 + fq * 8; const f32x4 g0 = *(const f32x4*)gp, g1 = *(const f32x4*)(gp + 4); UNPK8(raw[ks], x); u32x4 o;
;             o.x = cvt_pk_bf16(x[0] * rinv * g0[0], x[1] * rinv * g0[1]); o.y = cvt_pk_bf16(x[2] * rinv * g0[2], x[3] * rinv * g0[3]);
;             o.z = cvt_pk_bf16(x[4] * rinv * g1[0], x[5] * rinv * g1[1]); o.w = cvt_pk_bf16(x[6] * rinv * g1[2], x[7] * rinv * g1[3]);
;             bfr[tb][ks] = asfrag(o); }
; __global__ void __launch_bounds__(512, 2) fwd_kernel(KArgs a) {
;     ...
;             { IDS; const int SP = NGW - NGW / 8, rk = gw - (gw >> 3) - 1;
;               if (NGW != 2048) { for (int t = gw; t < nKV; t += NGW) kvproj_task(t, l, a.in[9], a.in[13], P, WUKV, KB, VT, fr, fq); }
;               else if (gw & 7) for (int t = rk; t < nKV; t += SP) kvproj_task(t, l, a.in[9], a.in[13], P, WUKV, KB, VT, fr, fq); }
.LBB0_424:
	s_andn2_b64 vcc, exec, s[4:5]
	s_cbranch_vccnz .LBB0_429
	s_ashr_i32 s1, s21, 3
	s_not_b32 s1, s1
	s_add_i32 s4, s21, s1
	s_and_b32 s1, s20, 0x1c0
	s_cmp_lg_u32 s1, 0
	s_cselect_b64 s[6:7], -1, 0
	s_cmpk_lt_i32 s4, 0x900
	s_cselect_b64 s[18:19], -1, 0
	s_and_b64 s[6:7], s[6:7], s[18:19]
	s_andn2_b64 vcc, exec, s[6:7]
	s_cbranch_vccnz .LBB0_429
	v_and_b32_e32 v5, 64, v199
	v_xor_b32_e32 v4, 16, v199
	v_add_u32_e32 v5, 64, v5
	v_cmp_lt_i32_e32 vcc, v4, v5
	v_readlane_b32 s14, v254, 27
	v_lshlrev_b32_e32 v2, 4, v214
	v_cndmask_b32_e32 v4, v199, v4, vcc
	v_lshlrev_b32_e32 v132, 2, v4
	v_xor_b32_e32 v4, 32, v199
	v_cmp_lt_i32_e32 vcc, v4, v5
	v_mov_b32_e32 v3, v1
	v_mov_b32_e32 v5, v1
	v_cndmask_b32_e32 v4, v199, v4, vcc
	v_lshlrev_b32_e32 v133, 2, v4
	v_lshlrev_b32_e32 v4, 5, v214
	v_readlane_b32 s15, v254, 28
	s_add_u32 s6, s42, 0x8eb8000
	s_addc_u32 s7, s43, 0
	v_lshl_add_u64 v[98:99], s[14:15], 0, v[4:5]
	v_lshl_add_u64 v[4:5], s[42:43], 0, v[2:3]
	s_mov_b64 s[14:15], 0x2260000
	v_lshl_add_u64 v[100:101], v[4:5], 0, s[14:15]
	v_readlane_b32 s14, v254, 30
	v_lshlrev_b32_e32 v0, 3, v214
	v_readlane_b32 s15, v254, 31
	v_lshl_add_u64 v[94:95], s[6:7], 0, v[2:3]
	v_lshlrev_b32_e32 v96, 2, v214
	v_lshl_add_u64 v[102:103], s[14:15], 0, v[2:3]
	v_lshl_add_u64 v[2:3], s[42:43], 0, v[0:1]
	s_mov_b64 s[14:15], 0x7838000
	v_lshl_add_u64 v[104:105], v[2:3], 0, s[14:15]
	v_and_b32_e32 v2, 4, v96
	v_cvt_f32_ubyte0_e32 v3, v2
	v_mul_f32_e32 v3, 0xbfd49a78, v3
	v_exp_f32_e32 v134, v3
	v_or_b32_e32 v3, 1, v2
	v_cvt_f32_ubyte0_e32 v3, v3
	v_mul_f32_e32 v3, 0xbfd49a78, v3
	v_exp_f32_e32 v135, v3
	v_or_b32_e32 v3, 2, v2
	v_or_b32_e32 v2, 3, v2
	v_cvt_f32_ubyte0_e32 v3, v3
	v_cvt_f32_ubyte0_e32 v2, v2
	v_mul_f32_e32 v3, 0xbfd49a78, v3
	v_mul_f32_e32 v2, 0xbfd49a78, v2
	v_exp_f32_e32 v136, v3
	v_exp_f32_e32 v137, v2
	v_readlane_b32 s1, v254, 29
	s_add_u32 s40, s42, 0x85b8000
	s_addc_u32 s41, s43, 0
	v_or_b32_e32 v2, s1, v97
	v_cmp_gt_u32_e64 s[36:37], 2, v214
	v_lshl_add_u64 v[106:107], s[6:7], 0, v[0:1]
	s_lshl_b32 s5, s4, 3
	v_lshlrev_b32_e32 v138, 7, v2
	v_readlane_b32 s14, v253, 30
	s_movk_i32 s15, 0xc0
	s_mov_b32 s18, 0x12000
	s_mov_b32 s19, 0x14000
	s_movk_i32 s20, 0x6000
	s_movk_i32 s21, 0x1000
	s_movk_i32 s22, 0x3000
	s_mov_b32 s23, 0x13000
	s_mov_b32 s24, 0x15000
	s_mov_b32 s25, 0x24000
	s_mov_b32 s26, 0x25000
	s_mov_b32 s27, 0x26000
	s_mov_b32 s42, 0x27000
	s_mov_b32 s43, 0x36000
	s_mov_b32 s44, 0x37000
	s_mov_b32 s45, 0x38000
	s_mov_b32 s46, 0x39000
	global_load_dwordx4 v[214:217], v[98:99], off
	global_load_dwordx4 v[218:221], v[98:99], off offset:16
	global_load_dwordx4 v[222:225], v[98:99], off offset:128
	global_load_dwordx4 v[226:229], v[98:99], off offset:144
	global_load_dwordx4 v[230:233], v[98:99], off offset:256
	global_load_dwordx4 v[234:237], v[98:99], off offset:272
	global_load_dwordx4 v[238:241], v[98:99], off offset:384
	global_load_dwordx4 v[242:245], v[98:99], off offset:400
	global_load_dwordx4 v[246:249], v[102:103], off
	global_load_dwordx4 v[176:179], v[102:103], off offset:64
	global_load_dwordx4 v[180:183], v[102:103], off offset:128
	global_load_dwordx4 v[184:187], v[102:103], off offset:192
	global_load_dwordx4 v[188:191], v[102:103], off offset:256
	s_nop 0
	s_nop 0
	s_nop 0
	s_nop 0
	s_nop 0
	s_nop 0
.LBB0_427:
	s_and_b32 s1, s5, 0xffffffe0
	v_or_b32_e32 v109, s1, v97
	v_mad_i64_i32 v[6:7], s[6:7], v109, s84, v[94:95]
	flat_load_dwordx4 v[14:17], v[6:7]
	flat_load_dwordx4 v[2:5], v[6:7] offset:64
	flat_load_dwordx4 v[40:43], v[6:7] offset:128
	flat_load_dwordx4 v[50:53], v[6:7] offset:192
	v_or_b32_e32 v111, 16, v109
	s_and_b32 s1, s4, 3
	s_add_i32 s4, s4, s14
	s_waitcnt vmcnt(0) lgkmcnt(0)
	v_and_b32_e32 v25, 0xffff0000, v15
	v_and_b32_e32 v29, 0xffff0000, v3
	v_and_b32_e32 v28, 0xffff0000, v2
	v_lshlrev_b32_e32 v31, 16, v3
	v_lshlrev_b32_e32 v30, 16, v2
	v_pk_mul_f32 v[2:3], v[28:29], v[28:29]
	v_and_b32_e32 v21, 0xffff0000, v5
	v_and_b32_e32 v20, 0xffff0000, v4
	v_pk_fma_f32 v[2:3], v[30:31], v[30:31], v[2:3]
	v_lshlrev_b32_e32 v27, 16, v5
	v_lshlrev_b32_e32 v26, 16, v4
	v_pk_mul_f32 v[4:5], v[20:21], v[20:21]
	v_pk_add_f32 v[2:3], v[2:3], v[2:3] op_sel:[0,1] op_sel_hi:[1,0]
	v_pk_fma_f32 v[44:45], v[26:27], v[26:27], v[4:5]
	v_and_b32_e32 v39, 0xffff0000, v14
	v_pk_add_f32 v[54:55], v[44:45], v[2:3]
	v_mad_i64_i32 v[2:3], s[6:7], v109, s84, v[106:107]
	flat_load_dwordx2 v[4:5], v[2:3] offset:256
	s_nop 0
	flat_load_dwordx2 v[2:3], v[2:3] offset:288
	v_and_b32_e32 v38, 0xffff0000, v16
	v_lshlrev_b32_e32 v24, 16, v15
	v_mul_f32_e32 v0, v25, v25
	v_lshlrev_b32_e32 v18, 16, v40
	v_and_b32_e32 v19, 0xffff0000, v40
	v_lshlrev_b32_e32 v8, 16, v41
	v_and_b32_e32 v9, 0xffff0000, v41
	v_lshlrev_b32_e32 v41, 16, v14
	v_lshlrev_b32_e32 v40, 16, v16
	v_pk_mul_f32 v[14:15], v[38:39], v[38:39]
	v_pk_fma_f32 v[22:23], v[24:25], v[24:25], v[0:1] op_sel_hi:[1,1,0]
	v_lshlrev_b32_e32 v7, 16, v53
	v_pk_fma_f32 v[14:15], v[40:41], v[40:41], v[14:15]
	v_mul_f32_e32 v6, v19, v19
	v_lshlrev_b32_e32 v36, 16, v17
	v_and_b32_e32 v37, 0xffff0000, v17
	v_lshlrev_b32_e32 v48, 16, v51
	v_and_b32_e32 v47, 0xffff0000, v51
	v_pk_add_f32 v[16:17], v[14:15], v[22:23] op_sel:[1,0] op_sel_hi:[0,1]
	v_lshlrev_b32_e32 v35, 16, v50
	v_and_b32_e32 v33, 0xffff0000, v50
	v_pk_fma_f32 v[50:51], v[18:19], v[18:19], v[6:7] op_sel_hi:[1,1,0]
	v_mul_f32_e32 v6, v9, v9
	v_and_b32_e32 v0, 0xffff0000, v53
	v_mul_f32_e32 v46, v48, v48
	v_mul_f32_e32 v49, v47, v47
	v_pk_add_f32 v[22:23], v[14:15], v[16:17]
	v_and_b32_e32 v32, 0xffff0000, v42
	v_pk_mov_b32 v[14:15], v[42:43], v[52:53] op_sel:[1,0]
	v_lshlrev_b32_e32 v17, 16, v52
	v_pk_fma_f32 v[52:53], v[8:9], v[8:9], v[6:7] op_sel_hi:[1,1,0]
	v_lshlrev_b32_e32 v34, 16, v42
	v_lshlrev_b32_e32 v16, 16, v43
	v_pk_mul_f32 v[42:43], v[32:33], v[32:33]
	v_mov_b32_e32 v51, v46
	v_mov_b32_e32 v53, v49
	v_and_b32_e32 v15, 0xffff0000, v15
	v_and_b32_e32 v14, 0xffff0000, v14
	v_pk_fma_f32 v[42:43], v[34:35], v[34:35], v[42:43]
	v_pk_add_f32 v[50:51], v[50:51], v[52:53]
	v_mul_f32_e32 v6, v37, v37
	v_pk_add_f32 v[42:43], v[42:43], v[50:51]
	v_pk_mul_f32 v[50:51], v[14:15], v[14:15]
	v_mov_b32_e32 v52, v22
	v_pk_fma_f32 v[50:51], v[16:17], v[16:17], v[50:51]
	v_mov_b32_e32 v53, v7
	v_pk_add_f32 v[42:43], v[50:51], v[42:43]
	v_pk_fma_f32 v[50:51], v[36:37], v[36:37], v[6:7] op_sel_hi:[1,1,0]
	v_mul_f32_e32 v56, v0, v0
	v_mov_b32_e32 v6, v50
	v_pk_add_f32 v[22:23], v[50:51], v[22:23]
	v_pk_mul_f32 v[50:51], v[6:7], v[52:53]
	v_pk_add_f32 v[44:45], v[44:45], v[54:55] op_sel:[1,0] op_sel_hi:[0,1]
	v_mov_b32_e32 v23, v51
	v_mov_b32_e32 v45, v56
	v_pk_add_f32 v[22:23], v[22:23], v[44:45]
	s_waitcnt vmcnt(0) lgkmcnt(0)
; __device__ __forceinline__ unsigned cvt_pk_bf16(float lo, float hi) { unsigned r; asm volatile("v_cvt_pk_bf16_f32 %0, %1, %2" : "=v"(r) : "v"(lo), "v"(hi)); return r; }
; __device__ __forceinline__ float bflo(unsigned w) { return __uint_as_float(w << 16); }
; __device__ __forceinline__ float bfhi(unsigned w) { return __uint_as_float(w & 0xffff0000u); }
; #define UNPK8(VV_, XX_) float XX_[8] = {bflo((VV_).x), bfhi((VV_).x), bflo((VV_).y), bfhi((VV_).y), bflo((VV_).z), bfhi((VV_).z), bflo((VV_).w), bfhi((VV_).w)}
; __device__ __forceinline__ void kvproj_task(int t, int l, const float* kvnorm, const float* kgain, const bf16_t* P, const bf16_t* WUKV, bf16_t* KB, bf16_t* VT, int fr, int fq) {
;     ...
;     for (int tb = 0; tb < 2; ++tb) { const int row = row0 + tb * 16; float ss = 0.f; u32x4 raw[4];
; #pragma unroll
;         for (int ks = 0; ks < 4; ++ks) { raw[ks] = ld8(P + (size_t)row * INP + ks * 32 + fq * 8); UNPK8(raw[ks], x);
;             ss += (x[0] * x[0] + x[1] * x[1]) + (x[2] * x[2] + x[3] * x[3]) + (x[4] * x[4] + x[5] * x[5]) + (x[6] * x[6] + x[7] * x[7]); }
; #pragma unroll
;         for (int cbr = 0; cbr < 2; ++cbr) { const u32x2 w = ld4(P + (size_t)row * INP + OFF_KROPE + cbr * 16 + fq * 4); kr[tb][cbr] = (f32x4){bflo(w.x), bfhi(w.x), bflo(w.y), bfhi(w.y)}; }
;         ss += __shfl_xor(ss, 16); ss += __shfl_xor(ss, 32);
;         const float rinv = rsqrtf(ss * (1.f / 128.f) + EPS);
; #pragma unroll
;         for (int ks = 0; ks < 4; ++ks) { const float* gp = kvnorm + l * 128 + ks * 32 + fq * 8; const f32x4 g0 = *(const f32x4*)gp, g1 = *(const f32x4*)(gp + 4); UNPK8(raw[ks], x); u32x4 o;
;             o.x = cvt_pk_bf16(x[0] * rinv * g0[0], x[1] * rinv * g0[1]); o.y = cvt_pk_bf16(x[2] * rinv * g0[2], x[3] * rinv * g0[3]);
;             o.z = cvt_pk_bf16(x[4] * rinv * g1[0], x[5] * rinv * g1[1]); o.w = cvt_pk_bf16(x[6] * rinv * g1[2], x[7] * rinv * g1[3]);
;             bfr[tb][ks] = asfrag(o); }
	v_and_b32_e32 v129, 0xffff0000, v5
	v_pk_add_f32 v[22:23], v[22:23], v[42:43]
	s_nop 0
	s_nop 0
	s_nop 0
	s_nop 0
	v_lshlrev_b32_e32 v120, 16, v3
	v_and_b32_e32 v122, 0xffff0000, v3
	v_add_f32_e32 v3, v22, v23
	ds_bpermute_b32 v6, v132, v3
	v_and_b32_e32 v128, 0xffff0000, v4
	v_lshlrev_b32_e32 v127, 16, v5
	v_lshlrev_b32_e32 v126, 16, v4
	v_pk_mul_f32 v[4:5], v[128:129], v[128:129]
	s_waitcnt lgkmcnt(0)
	v_add_f32_e32 v3, v3, v6
	ds_bpermute_b32 v6, v133, v3
	v_pk_fma_f32 v[130:131], v[126:127], v[126:127], v[4:5]
	v_lshlrev_b32_e32 v124, 16, v2
	v_and_b32_e32 v125, 0xffff0000, v2
	s_waitcnt lgkmcnt(0)
	v_add_f32_e32 v3, v3, v6
	v_fmamk_f32 v3, v3, 0x3c000000, v197
	v_cmp_gt_f32_e32 vcc, s47, v3
	v_mul_f32_e32 v6, 0x4b800000, v3
	s_nop 0
	v_cndmask_b32_e32 v3, v3, v6, vcc
	v_rsq_f32_e32 v3, v3
	s_nop 0
	v_mul_f32_e32 v6, 0x45800000, v3
	v_cndmask_b32_e32 v3, v3, v6, vcc
	v_mul_f32_e32 v6, v3, v41
	v_mul_f32_e32 v22, v3, v39
	v_mul_f32_e32 v23, v3, v25
	v_mul_f32_e32 v25, v3, v37
	v_mul_f32_e32 v28, v3, v28
	v_mul_f32_e32 v20, v3, v20
	v_mul_f32_e32 v0, v3, v0
	s_waitcnt vmcnt(1)
	v_mul_f32_e32 v25, v221, v25
	s_waitcnt vmcnt(0)
	v_mul_f32_e32 v6, v214, v6
	v_mul_f32_e32 v22, v215, v22
	v_cvt_pk_bf16_f32 v22, v6, v22
	v_mul_f32_e32 v6, v3, v24
	v_mul_f32_e32 v6, v216, v6
	v_mul_f32_e32 v23, v217, v23
	v_cvt_pk_bf16_f32 v23, v6, v23
	v_mul_f32_e32 v6, v3, v40
	v_mul_f32_e32 v24, v3, v38
	v_mul_f32_e32 v6, v218, v6
	v_mul_f32_e32 v24, v219, v24
	v_cvt_pk_bf16_f32 v24, v6, v24
	v_mul_f32_e32 v6, v3, v36
	v_mul_f32_e32 v6, v220, v6
	v_cvt_pk_bf16_f32 v25, v6, v25
	s_nop 0
	s_nop 0
	s_nop 0
	s_nop 0
	v_mul_f32_e32 v6, v3, v30
	s_waitcnt vmcnt(1)
	v_mul_f32_e32 v20, v227, v20
	s_waitcnt vmcnt(0)
	v_mul_f32_e32 v6, v222, v6
	v_mul_f32_e32 v28, v223, v28
	v_cvt_pk_bf16_f32 v38, v6, v28
	v_mul_f32_e32 v6, v3, v31
	v_mul_f32_e32 v6, v224, v6
	v_mul_f32_e32 v28, v3, v29
	v_mul_f32_e32 v28, v225, v28
	v_cvt_pk_bf16_f32 v39, v6, v28
	v_mul_f32_e32 v6, v3, v26
	v_mul_f32_e32 v6, v226, v6
	v_cvt_pk_bf16_f32 v40, v6, v20
	v_mul_f32_e32 v6, v3, v27
	v_mul_f32_e32 v20, v3, v21
	v_mul_f32_e32 v6, v228, v6
	v_mul_f32_e32 v20, v229, v20
	v_cvt_pk_bf16_f32 v41, v6, v20
	s_nop 0
	s_nop 0
	s_nop 0
	s_nop 0
	v_mul_f32_e32 v6, v3, v18
	v_mul_f32_e32 v18, v3, v19
	s_waitcnt vmcnt(0)
	v_mul_f32_e32 v6, v230, v6
	v_mul_f32_e32 v18, v231, v18
	v_cvt_pk_bf16_f32 v42, v6, v18
	v_mul_f32_e32 v6, v3, v8
	v_mul_f32_e32 v8, v3, v9
	v_mul_f32_e32 v6, v232, v6
	v_mul_f32_e32 v8, v233, v8
	v_cvt_pk_bf16_f32 v43, v6, v8
	v_mul_f32_e32 v6, v3, v34
	v_mul_f32_e32 v8, v3, v32
	v_mul_f32_e32 v6, v234, v6
	v_mul_f32_e32 v8, v235, v8
	v_cvt_pk_bf16_f32 v44, v6, v8
	v_mul_f32_e32 v6, v3, v16
	v_mul_f32_e32 v8, v3, v14
	v_mul_f32_e32 v6, v236, v6
	v_mul_f32_e32 v8, v237, v8
	v_cvt_pk_bf16_f32 v45, v6, v8
	s_nop 0
	s_nop 0
	s_nop 0
	s_nop 0
	v_mul_f32_e32 v6, v3, v35
	v_mul_f32_e32 v8, v3, v33
	s_waitcnt vmcnt(1)
	v_mul_f32_e32 v0, v0, v245
	s_waitcnt vmcnt(0)
	v_mul_f32_e32 v6, v6, v238
	v_mul_f32_e32 v8, v8, v239
	v_cvt_pk_bf16_f32 v46, v6, v8
	v_mul_f32_e32 v6, v3, v48
	v_mul_f32_e32 v6, v6, v240
	v_mul_f32_e32 v8, v3, v47
	v_mul_f32_e32 v8, v8, v241
	v_cvt_pk_bf16_f32 v47, v6, v8
	v_mul_f32_e32 v6, v3, v17
	v_mul_f32_e32 v6, v6, v242
	v_mul_f32_e32 v8, v3, v15
	v_mul_f32_e32 v8, v8, v243
	v_cvt_pk_bf16_f32 v48, v6, v8
	v_mul_f32_e32 v6, v3, v7
	v_mul_f32_e32 v6, v6, v244
	v_mad_i64_i32 v[14:15], s[6:7], v111, s84, v[94:95]
	v_cvt_pk_bf16_f32 v49, v6, v0
	flat_load_dwordx4 v[2:5], v[14:15]
	flat_load_dwordx4 v[6:9], v[14:15] offset:64
	s_waitcnt vmcnt(0) lgkmcnt(0)
	v_and_b32_e32 v19, 0xffff0000, v3
	v_and_b32_e32 v31, 0xffff0000, v7
	v_and_b32_e32 v30, 0xffff0000, v6
	v_lshlrev_b32_e32 v29, 16, v7
	v_lshlrev_b32_e32 v28, 16, v6
	v_pk_mul_f32 v[6:7], v[30:31], v[30:31]
	v_and_b32_e32 v35, 0xffff0000, v9
	v_and_b32_e32 v34, 0xffff0000, v8
	v_pk_fma_f32 v[6:7], v[28:29], v[28:29], v[6:7]
	v_lshlrev_b32_e32 v33, 16, v9
	v_lshlrev_b32_e32 v32, 16, v8
	v_pk_mul_f32 v[8:9], v[34:35], v[34:35]
	v_pk_add_f32 v[6:7], v[6:7], v[6:7] op_sel:[0,1] op_sel_hi:[1,0]
	v_pk_fma_f32 v[36:37], v[32:33], v[32:33], v[8:9]
	v_and_b32_e32 v55, 0xffff0000, v2
	v_pk_add_f32 v[50:51], v[36:37], v[6:7]
	flat_load_dwordx4 v[6:9], v[14:15] offset:128
	v_and_b32_e32 v54, 0xffff0000, v4
	flat_load_dwordx4 v[14:17], v[14:15] offset:192
	v_lshlrev_b32_e32 v18, 16, v3
	v_mul_f32_e32 v0, v19, v19
	v_lshlrev_b32_e32 v53, 16, v2
	v_lshlrev_b32_e32 v52, 16, v4
	v_pk_mul_f32 v[2:3], v[54:55], v[54:55]
	v_pk_fma_f32 v[20:21], v[18:19], v[18:19], v[0:1] op_sel_hi:[1,1,0]
	v_pk_fma_f32 v[2:3], v[52:53], v[52:53], v[2:3]
	v_lshlrev_b32_e32 v26, 16, v5
	v_and_b32_e32 v27, 0xffff0000, v5
	v_pk_add_f32 v[4:5], v[2:3], v[20:21] op_sel:[1,0] op_sel_hi:[0,1]
	v_pk_add_f32 v[2:3], v[2:3], v[4:5]
	s_waitcnt vmcnt(0) lgkmcnt(0)
; __device__ __forceinline__ unsigned cvt_pk_bf16(float lo, float hi) { unsigned r; asm volatile("v_cvt_pk_bf16_f32 %0, %1, %2" : "=v"(r) : "v"(lo), "v"(hi)); return r; }
; __device__ __forceinline__ void kvproj_task(int t, int l, const float* kvnorm, const float* kgain, const bf16_t* P, const bf16_t* WUKV, bf16_t* KB, bf16_t* VT, int fr, int fq) {
;     ...
;     for (int tb = 0; tb < 2; ++tb) { const int row = row0 + tb * 16; float ss = 0.f; u32x4 raw[4];
; #pragma unroll
;         for (int ks = 0; ks < 4; ++ks) { raw[ks] = ld8(P + (size_t)row * INP + ks * 32 + fq * 8); UNPK8(raw[ks], x);
;             ss += (x[0] * x[0] + x[1] * x[1]) + (x[2] * x[2] + x[3] * x[3]) + (x[4] * x[4] + x[5] * x[5]) + (x[6] * x[6] + x[7] * x[7]); }
; #pragma unroll
;         for (int cbr = 0; cbr < 2; ++cbr) { const u32x2 w = ld4(P + (size_t)row * INP + OFF_KROPE + cbr * 16 + fq * 4); kr[tb][cbr] = (f32x4){bflo(w.x), bfhi(w.x), bflo(w.y), bfhi(w.y)}; }
;         ss += __shfl_xor(ss, 16); ss += __shfl_xor(ss, 32);
;         const float rinv = rsqrtf(ss * (1.f / 128.f) + EPS);
; #pragma unroll
;         for (int ks = 0; ks < 4; ++ks) { const float* gp = kvnorm + l * 128 + ks * 32 + fq * 8; const f32x4 g0 = *(const f32x4*)gp, g1 = *(const f32x4*)(gp + 4); UNPK8(raw[ks], x); u32x4 o;
;             o.x = cvt_pk_bf16(x[0] * rinv * g0[0], x[1] * rinv * g0[1]); o.y = cvt_pk_bf16(x[2] * rinv * g0[2], x[3] * rinv * g0[3]);
;             o.z = cvt_pk_bf16(x[4] * rinv * g1[0], x[5] * rinv * g1[1]); o.w = cvt_pk_bf16(x[6] * rinv * g1[2], x[7] * rinv * g1[3]);
;             bfr[tb][ks] = asfrag(o); }
;         skr[tb] = (kr[tb][0][0] * kr[tb][0][0] + kr[tb][0][1] * kr[tb][0][1]) + (kr[tb][0][2] * kr[tb][0][2] + kr[tb][0][3] * kr[tb][0][3]) + (kr[tb][1][0] * kr[tb][1][0] + kr[tb][1][1] * kr[tb][1][1]) + (kr[tb][1][2] * kr[tb][1][2] + kr[tb][1][3] * kr[tb][1][3]); }
;     const bf16_t* wk0 = WUKV + ((size_t)l * 512 + h * 128 + fr) * 128 + fq * 8;
;     bf16x8 wf[2][4];
; #pragma unroll
;     for (int ks = 0; ks < 4; ++ks) wf[0][ks] = asfrag(ld8(wk0 + ks * 32));
;     f32x4 acc[2][8];
; #pragma unroll
;     for (int cb = 0; cb < 8; ++cb) { acc[0][cb] = (f32x4){0.f, 0.f, 0.f, 0.f}; acc[1][cb] = acc[0][cb];
;         const int nrow = cb < 7 ? (cb + 1) * 16 : 0;
; #pragma unroll
;         for (int ks = 0; ks < 4; ++ks) wf[(cb + 1) & 1][ks] = asfrag(ld8(wk0 + (size_t)nrow * 128 + ks * 32));
	v_and_b32_e32 v59, 0xffff0000, v6
	v_lshlrev_b32_e32 v58, 16, v6
	v_lshlrev_b32_e32 v60, 16, v7
	v_and_b32_e32 v61, 0xffff0000, v7
	v_mad_i64_i32 v[6:7], s[6:7], v111, s84, v[106:107]
	v_mul_f32_e32 v0, v59, v59
	v_lshlrev_b32_e32 v70, 16, v15
	v_and_b32_e32 v71, 0xffff0000, v15
	flat_load_dwordx2 v[66:67], v[6:7] offset:256
	flat_load_dwordx2 v[68:69], v[6:7] offset:288
	v_pk_fma_f32 v[6:7], v[58:59], v[58:59], v[0:1] op_sel_hi:[1,1,0]
	v_mul_f32_e32 v0, v61, v61
	v_lshlrev_b32_e32 v15, 16, v17
	v_and_b32_e32 v72, 0xffff0000, v17
	v_mul_f32_e32 v56, v70, v70
	v_mul_f32_e32 v57, v71, v71
	v_lshlrev_b32_e32 v20, 16, v8
	v_and_b32_e32 v63, 0xffff0000, v14
	v_and_b32_e32 v62, 0xffff0000, v8
	v_pk_mov_b32 v[4:5], v[8:9], v[16:17] op_sel:[1,0]
	v_lshlrev_b32_e32 v17, 16, v16
	v_lshlrev_b32_e32 v16, 16, v9
	v_pk_fma_f32 v[8:9], v[60:61], v[60:61], v[0:1] op_sel_hi:[1,1,0]
	v_lshlrev_b32_e32 v21, 16, v14
	v_and_b32_e32 v65, 0xffff0000, v5
	v_and_b32_e32 v64, 0xffff0000, v4
	v_pk_mul_f32 v[4:5], v[62:63], v[62:63]
	v_mov_b32_e32 v7, v56
	v_mov_b32_e32 v9, v57
	v_pk_fma_f32 v[4:5], v[20:21], v[20:21], v[4:5]
	v_pk_add_f32 v[6:7], v[6:7], v[8:9]
	v_mul_f32_e32 v0, v27, v27
	v_pk_add_f32 v[4:5], v[4:5], v[6:7]
	v_pk_mul_f32 v[6:7], v[64:65], v[64:65]
	v_mov_b32_e32 v8, v2
	v_pk_fma_f32 v[6:7], v[16:17], v[16:17], v[6:7]
	v_mov_b32_e32 v9, v15
	v_pk_add_f32 v[4:5], v[6:7], v[4:5]
	v_pk_fma_f32 v[6:7], v[26:27], v[26:27], v[0:1] op_sel_hi:[1,1,0]
	v_mul_f32_e32 v73, v72, v72
	v_mov_b32_e32 v14, v6
	v_pk_add_f32 v[2:3], v[6:7], v[2:3]
	v_pk_mul_f32 v[6:7], v[14:15], v[8:9]
	s_movk_i32 s6, 0x5000
	v_mov_b32_e32 v3, v7
	v_pk_add_f32 v[6:7], v[36:37], v[50:51] op_sel:[1,0] op_sel_hi:[0,1]
	v_mov_b32_e32 v7, v73
	v_pk_add_f32 v[2:3], v[2:3], v[6:7]
	s_waitcnt vmcnt(0) lgkmcnt(0)
	v_and_b32_e32 v117, 0xffff0000, v67
	v_pk_add_f32 v[2:3], v[2:3], v[4:5]
	v_and_b32_e32 v116, 0xffff0000, v66
	v_add_f32_e32 v0, v2, v3
	ds_bpermute_b32 v2, v132, v0
	v_lshlrev_b32_e32 v115, 16, v67
	v_lshlrev_b32_e32 v114, 16, v66
	v_lshlrev_b32_e32 v108, 16, v69
	v_and_b32_e32 v110, 0xffff0000, v69
	s_waitcnt lgkmcnt(0)
	v_add_f32_e32 v0, v0, v2
	ds_bpermute_b32 v2, v133, v0
	v_lshlrev_b32_e32 v112, 16, v68
	v_and_b32_e32 v113, 0xffff0000, v68
	s_waitcnt lgkmcnt(0)
	v_add_f32_e32 v0, v0, v2
	v_fmamk_f32 v0, v0, 0x3c000000, v197
	v_cmp_gt_f32_e32 vcc, s47, v0
	v_mul_f32_e32 v2, 0x4b800000, v0
	s_nop 0
	v_cndmask_b32_e32 v0, v0, v2, vcc
	v_rsq_f32_e32 v0, v0
	s_nop 0
	v_mul_f32_e32 v2, 0x45800000, v0
	v_cndmask_b32_e32 v0, v0, v2, vcc
	s_nop 0
	s_nop 0
	s_nop 0
	s_nop 0
	v_mul_f32_e32 v14, v0, v53
	s_waitcnt vmcnt(0)
	v_mul_f32_e32 v6, v214, v14
	v_mul_f32_e32 v14, v0, v55
	v_mul_f32_e32 v7, v215, v14
	v_cvt_pk_bf16_f32 v50, v6, v7
	v_mul_f32_e32 v6, v0, v18
	v_mul_f32_e32 v6, v216, v6
	v_mul_f32_e32 v7, v0, v19
	v_mul_f32_e32 v7, v217, v7
	v_cvt_pk_bf16_f32 v51, v6, v7
	v_mul_f32_e32 v6, v0, v52
	v_mul_f32_e32 v2, v218, v6
	v_mul_f32_e32 v6, v0, v54
	v_mul_f32_e32 v3, v219, v6
	v_cvt_pk_bf16_f32 v52, v2, v3
	v_mul_f32_e32 v2, v0, v26
	v_mul_f32_e32 v3, v0, v27
	v_mul_f32_e32 v2, v220, v2
	v_mul_f32_e32 v3, v221, v3
	v_cvt_pk_bf16_f32 v53, v2, v3
	s_nop 0
	s_nop 0
	s_nop 0
	s_nop 0
	v_mul_f32_e32 v14, v0, v28
	s_waitcnt vmcnt(0)
	v_mul_f32_e32 v6, v222, v14
	v_mul_f32_e32 v14, v0, v30
	v_mul_f32_e32 v7, v223, v14
	v_cvt_pk_bf16_f32 v54, v6, v7
	v_mul_f32_e32 v6, v0, v29
	v_mul_f32_e32 v6, v224, v6
	v_mul_f32_e32 v7, v0, v31
	v_mul_f32_e32 v7, v225, v7
	v_cvt_pk_bf16_f32 v55, v6, v7
	v_mul_f32_e32 v6, v0, v32
	v_mul_f32_e32 v2, v226, v6
	v_mul_f32_e32 v6, v0, v34
	v_mul_f32_e32 v3, v227, v6
	v_cvt_pk_bf16_f32 v56, v2, v3
	v_mul_f32_e32 v2, v0, v33
	v_mul_f32_e32 v3, v0, v35
	v_mul_f32_e32 v2, v228, v2
	v_mul_f32_e32 v3, v229, v3
	v_cvt_pk_bf16_f32 v57, v2, v3
	s_nop 0
	s_nop 0
	s_nop 0
	s_nop 0
	v_mul_f32_e32 v14, v0, v58
	s_waitcnt vmcnt(0)
	v_mul_f32_e32 v6, v230, v14
	v_mul_f32_e32 v14, v0, v59
	v_mul_f32_e32 v7, v231, v14
	v_cvt_pk_bf16_f32 v58, v6, v7
	v_mul_f32_e32 v6, v0, v60
	v_mul_f32_e32 v6, v232, v6
	v_mul_f32_e32 v7, v0, v61
	v_mul_f32_e32 v7, v233, v7
	v_cvt_pk_bf16_f32 v59, v6, v7
	v_mul_f32_e32 v6, v0, v20
	v_mul_f32_e32 v2, v234, v6
	v_mul_f32_e32 v6, v0, v62
	v_mul_f32_e32 v3, v235, v6
	v_cvt_pk_bf16_f32 v60, v2, v3
	v_mul_f32_e32 v2, v0, v16
	v_mul_f32_e32 v3, v0, v64
	v_mul_f32_e32 v2, v236, v2
	v_mul_f32_e32 v3, v237, v3
	v_cvt_pk_bf16_f32 v61, v2, v3
	s_nop 0
	s_nop 0
	s_nop 0
	s_nop 0
	v_mul_f32_e32 v14, v0, v21
	s_waitcnt vmcnt(0)
	v_mul_f32_e32 v6, v14, v238
	v_mul_f32_e32 v14, v0, v63
	v_mul_f32_e32 v7, v14, v239
	v_cvt_pk_bf16_f32 v62, v6, v7
	v_mul_f32_e32 v6, v0, v70
	v_mul_f32_e32 v6, v6, v240
	v_mul_f32_e32 v7, v0, v71
	v_mul_f32_e32 v7, v7, v241
	v_cvt_pk_bf16_f32 v63, v6, v7
	v_mul_f32_e32 v6, v0, v17
	v_mul_f32_e32 v2, v6, v242
	v_mul_f32_e32 v6, v0, v65
	v_mul_f32_e32 v3, v6, v243
	v_cvt_pk_bf16_f32 v64, v2, v3
	v_mul_f32_e32 v2, v0, v15
	v_mul_f32_e32 v0, v0, v72
	v_mul_f32_e32 v0, v0, v245
	v_mul_f32_e32 v2, v2, v244
	v_cvt_pk_bf16_f32 v65, v2, v0
	v_lshl_or_b32 v0, s1, 14, v138
	v_pk_mul_f32 v[2:3], v[116:117], v[116:117]
	v_lshl_add_u64 v[148:149], v[0:1], 1, v[100:101]
	v_pk_fma_f32 v[118:119], v[114:115], v[114:115], v[2:3]
	flat_load_dwordx4 v[2:5], v[148:149]
	flat_load_dwordx4 v[6:9], v[148:149] offset:64
	flat_load_dwordx4 v[14:17], v[148:149] offset:128
	flat_load_dwordx4 v[18:21], v[148:149] offset:192
	v_add_co_u32_e32 v26, vcc, s21, v148
	v_add_u32_e32 v0, 0xffffc000, v109
	s_nop 0
	v_addc_co_u32_e32 v27, vcc, 0, v149, vcc
	flat_load_dwordx4 v[30:33], v[26:27]
	flat_load_dwordx4 v[34:37], v[26:27] offset:64
	flat_load_dwordx4 v[66:69], v[26:27] offset:128
	flat_load_dwordx4 v[74:77], v[26:27] offset:192
	s_waitcnt vmcnt(0) lgkmcnt(0)
; #define MFMA16(a, b, c) __builtin_amdgcn_mfma_f32_16x16x32_bf16((a), (b), (c), 0, 0, 0)
; __device__ __forceinline__ void kvproj_task(int t, int l, const float* kvnorm, const float* kgain, const bf16_t* P, const bf16_t* WUKV, bf16_t* KB, bf16_t* VT, int fr, int fq) {
;     ...
;     f32x4 acc[2][8];
; #pragma unroll
;     for (int cb = 0; cb < 8; ++cb) { acc[0][cb] = (f32x4){0.f, 0.f, 0.f, 0.f}; acc[1][cb] = acc[0][cb];
;         const int nrow = cb < 7 ? (cb + 1) * 16 : 0;
; #pragma unroll
;         for (int ks = 0; ks < 4; ++ks) wf[(cb + 1) & 1][ks] = asfrag(ld8(wk0 + (size_t)nrow * 128 + ks * 32));
; #pragma unroll
;         for (int ks = 0; ks < 4; ++ks) { acc[0][cb] = MFMA16(wf[cb & 1][ks], bfr[0][ks], acc[0][cb]); acc[1][cb] = MFMA16(wf[cb & 1][ks], bfr[1][ks], acc[1][cb]); } }
	v_mfma_f32_16x16x32_bf16 v[26:29], v[2:5], v[22:25], 0
	v_mfma_f32_16x16x32_bf16 v[2:5], v[2:5], v[50:53], 0
	v_mfma_f32_16x16x32_bf16 v[26:29], v[6:9], v[38:41], v[26:29]
	v_mfma_f32_16x16x32_bf16 v[2:5], v[6:9], v[54:57], v[2:5]
	v_mfma_f32_16x16x32_bf16 v[6:9], v[14:17], v[42:45], v[26:29]
	v_mfma_f32_16x16x32_bf16 v[2:5], v[14:17], v[58:61], v[2:5]
	v_mfma_f32_16x16x32_bf16 v[70:73], v[18:21], v[46:49], v[6:9]
	v_mfma_f32_16x16x32_bf16 v[26:29], v[18:21], v[62:65], v[2:5]
	v_add_co_u32_e32 v18, vcc, s33, v148
	s_nop 5
	v_mov_b32_e32 v123, v71
	v_addc_co_u32_e32 v19, vcc, 0, v149, vcc
	flat_load_dwordx4 v[2:5], v[18:19]
	flat_load_dwordx4 v[6:9], v[18:19] offset:64
	flat_load_dwordx4 v[14:17], v[18:19] offset:128
	flat_load_dwordx4 v[86:89], v[18:19] offset:192
	v_mfma_f32_16x16x32_bf16 v[18:21], v[30:33], v[22:25], 0
	v_mov_b32_e32 v121, v70
	v_mfma_f32_16x16x32_bf16 v[30:33], v[30:33], v[50:53], 0
	v_mfma_f32_16x16x32_bf16 v[18:21], v[34:37], v[38:41], v[18:21]
	v_mfma_f32_16x16x32_bf16 v[30:33], v[34:37], v[54:57], v[30:33]
	v_mfma_f32_16x16x32_bf16 v[18:21], v[66:69], v[42:45], v[18:21]
	v_mfma_f32_16x16x32_bf16 v[30:33], v[66:69], v[58:61], v[30:33]
	v_mfma_f32_16x16x32_bf16 v[78:81], v[74:77], v[46:49], v[18:21]
	v_mfma_f32_16x16x32_bf16 v[18:21], v[74:77], v[62:65], v[30:33]
	v_add_co_u32_e32 v74, vcc, s22, v148
	s_nop 1
	v_addc_co_u32_e32 v75, vcc, 0, v149, vcc
	s_nop 1
	flat_load_dwordx4 v[30:33], v[74:75]
	flat_load_dwordx4 v[34:37], v[74:75] offset:64
	flat_load_dwordx4 v[66:69], v[74:75] offset:128
	s_nop 0
	flat_load_dwordx4 v[74:77], v[74:75] offset:192
	s_waitcnt vmcnt(0) lgkmcnt(0)
	v_mfma_f32_16x16x32_bf16 v[82:85], v[2:5], v[22:25], 0
	v_mfma_f32_16x16x32_bf16 v[2:5], v[2:5], v[50:53], 0
	v_mfma_f32_16x16x32_bf16 v[82:85], v[6:9], v[38:41], v[82:85]
	v_mfma_f32_16x16x32_bf16 v[2:5], v[6:9], v[54:57], v[2:5]
	v_mfma_f32_16x16x32_bf16 v[6:9], v[14:17], v[42:45], v[82:85]
	v_mfma_f32_16x16x32_bf16 v[2:5], v[14:17], v[58:61], v[2:5]
	v_mfma_f32_16x16x32_bf16 v[82:85], v[86:89], v[46:49], v[6:9]
	v_mfma_f32_16x16x32_bf16 v[14:17], v[86:89], v[62:65], v[2:5]
	v_add_co_u32_e32 v86, vcc, s0, v148
	s_nop 1
	v_addc_co_u32_e32 v87, vcc, 0, v149, vcc
	s_nop 1
	flat_load_dwordx4 v[2:5], v[86:87]
	flat_load_dwordx4 v[6:9], v[86:87] offset:64
	flat_load_dwordx4 v[90:93], v[86:87] offset:128
	flat_load_dwordx4 v[140:143], v[86:87] offset:192
	v_mfma_f32_16x16x32_bf16 v[86:89], v[30:33], v[22:25], 0
	v_mfma_f32_16x16x32_bf16 v[30:33], v[30:33], v[50:53], 0
	v_mfma_f32_16x16x32_bf16 v[86:89], v[34:37], v[38:41], v[86:89]
	v_mfma_f32_16x16x32_bf16 v[30:33], v[34:37], v[54:57], v[30:33]
	v_mfma_f32_16x16x32_bf16 v[34:37], v[66:69], v[42:45], v[86:89]
	v_mfma_f32_16x16x32_bf16 v[30:33], v[66:69], v[58:61], v[30:33]
	v_mfma_f32_16x16x32_bf16 v[86:89], v[74:77], v[46:49], v[34:37]
	v_mfma_f32_16x16x32_bf16 v[30:33], v[74:77], v[62:65], v[30:33]
	v_add_co_u32_e32 v74, vcc, s6, v148
	s_movk_i32 s6, 0x7000
	s_nop 0
	v_addc_co_u32_e32 v75, vcc, 0, v149, vcc
	s_nop 0
	flat_load_dwordx4 v[34:37], v[74:75]
	flat_load_dwordx4 v[66:69], v[74:75] offset:64
	flat_load_dwordx4 v[144:147], v[74:75] offset:128
	flat_load_dwordx4 v[156:159], v[74:75] offset:192
	s_waitcnt vmcnt(0) lgkmcnt(0)
	v_mfma_f32_16x16x32_bf16 v[74:77], v[2:5], v[22:25], 0
	v_mfma_f32_16x16x32_bf16 v[2:5], v[2:5], v[50:53], 0
	v_mfma_f32_16x16x32_bf16 v[74:77], v[6:9], v[38:41], v[74:77]
	v_mfma_f32_16x16x32_bf16 v[2:5], v[6:9], v[54:57], v[2:5]
	v_mfma_f32_16x16x32_bf16 v[6:9], v[90:93], v[42:45], v[74:77]
	v_mfma_f32_16x16x32_bf16 v[2:5], v[90:93], v[58:61], v[2:5]
	v_mfma_f32_16x16x32_bf16 v[74:77], v[140:143], v[46:49], v[6:9]
	v_mfma_f32_16x16x32_bf16 v[6:9], v[140:143], v[62:65], v[2:5]
	s_nop 5
	v_add_co_u32_e32 v2, vcc, s20, v148
	s_nop 1
	v_addc_co_u32_e32 v3, vcc, 0, v149, vcc
	flat_load_dwordx4 v[90:93], v[2:3]
	flat_load_dwordx4 v[140:143], v[2:3] offset:64
	flat_load_dwordx4 v[160:163], v[2:3] offset:128
	flat_load_dwordx4 v[164:167], v[2:3] offset:192
	v_mfma_f32_16x16x32_bf16 v[2:5], v[34:37], v[22:25], 0
	v_mfma_f32_16x16x32_bf16 v[34:37], v[34:37], v[50:53], 0
	v_mfma_f32_16x16x32_bf16 v[2:5], v[66:69], v[38:41], v[2:5]
	v_mfma_f32_16x16x32_bf16 v[34:37], v[66:69], v[54:57], v[34:37]
	v_mfma_f32_16x16x32_bf16 v[2:5], v[144:147], v[42:45], v[2:5]
	v_mfma_f32_16x16x32_bf16 v[34:37], v[144:147], v[58:61], v[34:37]
	v_mfma_f32_16x16x32_bf16 v[66:69], v[156:159], v[46:49], v[2:5]
	v_mfma_f32_16x16x32_bf16 v[2:5], v[156:159], v[62:65], v[34:37]
	s_nop 5
	v_add_co_u32_e32 v34, vcc, s6, v148
	s_nop 1
	v_addc_co_u32_e32 v35, vcc, 0, v149, vcc
	flat_load_dwordx4 v[144:147], v[34:35]
	flat_load_dwordx4 v[156:159], v[34:35] offset:64
	flat_load_dwordx4 v[168:171], v[34:35] offset:128
	flat_load_dwordx4 v[172:175], v[34:35] offset:192
	s_waitcnt vmcnt(0) lgkmcnt(0)
; __device__ __forceinline__ unsigned cvt_pk_bf16(float lo, float hi) { unsigned r; asm volatile("v_cvt_pk_bf16_f32 %0, %1, %2" : "=v"(r) : "v"(lo), "v"(hi)); return r; }
; #define MFMA16(a, b, c) __builtin_amdgcn_mfma_f32_16x16x32_bf16((a), (b), (c), 0, 0, 0)
; __device__ __forceinline__ void kvproj_task(int t, int l, const float* kvnorm, const float* kgain, const bf16_t* P, const bf16_t* WUKV, bf16_t* KB, bf16_t* VT, int fr, int fq) {
;     ...
;         for (int ks = 0; ks < 4; ++ks) { acc[0][cb] = MFMA16(wf[cb & 1][ks], bfr[0][ks], acc[0][cb]); acc[1][cb] = MFMA16(wf[cb & 1][ks], bfr[1][ks], acc[1][cb]); } }
; #pragma unroll
;     for (int tb = 0; tb < 2; ++tb) { const int row = row0 + tb * 16, rr = isc ? row - ML : row;
;         const int b = isc ? rr >> 8 : rr >> 11, tpos = isc ? rr & 255 : rr & 2047, key = isc ? tpos : 256 + tpos;
;         float s2 = skr[tb];
; #pragma unroll
;         for (int cb = 0; cb < 4; ++cb) s2 += (acc[tb][cb][0] * acc[tb][cb][0] + acc[tb][cb][1] * acc[tb][cb][1]) + (acc[tb][cb][2] * acc[tb][cb][2] + acc[tb][cb][3] * acc[tb][cb][3]);
;         s2 += __shfl_xor(s2, 16); s2 += __shfl_xor(s2, 32);
;         const float rh = rsqrtf(s2 * (1.f / 96.f) + EPS);
;         bf16_t* kdst = KB + ((size_t)(b * 4 + h) * NKEY + key) * 96;
; #pragma unroll
;         for (int cb = 0; cb < 6; ++cb) { const f32x4 kg = *(const f32x4*)(kgain + l * 96 + cb * 16 + fq * 4); f32x4 v = (cb < 4 ? acc[tb][cb < 4 ? cb : 0] : kr[tb][cb >= 4 ? cb - 4 : 0]) * rh * kg;
;             if (cb >= 4) { const f32x4 rv = rope16(v, fq, (float)(cb == 4 ? (tpos >> 6) : (tpos & 63))); if (!isc) v = rv; }
;             u32x2 w; w.x = cvt_pk_bf16(v[0], v[1]); w.y = cvt_pk_bf16(v[2], v[3]);
;             *(u32x2*)(kdst + cb * 16 + fq * 4) = w; }
	v_mfma_f32_16x16x32_bf16 v[34:37], v[90:93], v[22:25], 0
	v_cmp_lt_i32_e32 vcc, s49, v109
	v_mfma_f32_16x16x32_bf16 v[22:25], v[144:147], v[22:25], 0
	v_mfma_f32_16x16x32_bf16 v[90:93], v[90:93], v[50:53], 0
	v_mfma_f32_16x16x32_bf16 v[50:53], v[144:147], v[50:53], 0
	v_mfma_f32_16x16x32_bf16 v[34:37], v[140:143], v[38:41], v[34:37]
	v_mfma_f32_16x16x32_bf16 v[22:25], v[156:159], v[38:41], v[22:25]
	v_mfma_f32_16x16x32_bf16 v[38:41], v[156:159], v[54:57], v[50:53]
	v_mfma_f32_16x16x32_bf16 v[90:93], v[140:143], v[54:57], v[90:93]
	v_cndmask_b32_e32 v54, v109, v0, vcc
	v_mul_f32_e32 v0, v72, v72
	s_nop 1
	v_mul_f32_e32 v50, v73, v73
	v_mfma_f32_16x16x32_bf16 v[34:37], v[160:163], v[42:45], v[34:37]
	v_mfma_f32_16x16x32_bf16 v[22:25], v[168:171], v[42:45], v[22:25]
	v_mfma_f32_16x16x32_bf16 v[42:45], v[168:171], v[58:61], v[38:41]
	v_mfma_f32_16x16x32_bf16 v[140:143], v[160:163], v[58:61], v[90:93]
	v_mfma_f32_16x16x32_bf16 v[90:93], v[164:167], v[46:49], v[34:37]
	v_mfma_f32_16x16x32_bf16 v[38:41], v[172:175], v[46:49], v[22:25]
	v_add_f32_e64 v46, v130, v131
	v_add_f32_e64 v47, v131, v130
	v_mov_b32_e32 v47, v0
	v_mul_f32_e32 v0, v125, v125
	v_pk_fma_f32 v[48:49], v[124:125], v[124:125], v[0:1] op_sel_hi:[1,1,0]
	v_mfma_f32_16x16x32_bf16 v[22:25], v[172:175], v[62:65], v[42:45]
	v_mov_b32_e32 v49, v50
	v_pk_add_f32 v[46:47], v[46:47], v[48:49]
	v_pk_mul_f32 v[48:49], v[78:79], v[78:79]
	v_pk_mul_f32 v[44:45], v[122:123], v[122:123]
	v_mul_f32_e32 v0, v86, v86
	v_pk_fma_f32 v[44:45], v[120:121], v[120:121], v[44:45]
	v_cndmask_b32_e32 v43, v200, v201, vcc
	v_pk_add_f32 v[44:45], v[44:45], v[46:47]
	v_pk_mul_f32 v[46:47], v[80:81], v[80:81]
	v_pk_add_f32 v[44:45], v[44:45], v[44:45] op_sel:[0,1] op_sel_hi:[1,0]
	v_pk_mov_b32 v[50:51], v[48:49], v[46:47] op_sel:[1,0]
	v_mov_b32_e32 v49, v47
	v_pk_add_f32 v[46:47], v[50:51], v[48:49]
	v_mul_f32_e32 v48, v87, v87
	v_pk_add_f32 v[46:47], v[46:47], v[46:47] op_sel:[0,1] op_sel_hi:[1,0]
	v_mov_b32_e32 v45, v0
	v_mov_b32_e32 v47, v48
	v_mul_f32_e32 v0, v83, v83
	v_mul_f32_e32 v49, v88, v88
	v_pk_add_f32 v[44:45], v[44:45], v[46:47]
	v_pk_fma_f32 v[46:47], v[82:83], v[82:83], v[0:1] op_sel_hi:[1,1,0]
	v_mul_f32_e32 v0, v85, v85
	v_mul_f32_e32 v50, v89, v89
	v_mov_b32_e32 v47, v49
	v_pk_fma_f32 v[48:49], v[84:85], v[84:85], v[0:1] op_sel_hi:[1,1,0]
	v_cndmask_b32_e64 v42, 11, 8, vcc
	v_mov_b32_e32 v49, v50
	v_pk_add_f32 v[46:47], v[46:47], v[48:49]
	v_and_b32_e32 v55, v54, v43
	v_pk_add_f32 v[44:45], v[44:45], v[46:47]
	v_add_u32_e32 v52, 0x100, v55
	v_add_f32_e32 v44, v44, v45
	ds_bpermute_b32 v46, v132, v44
	v_ashrrev_i32_e32 v45, v42, v54
	v_cndmask_b32_e32 v0, v52, v55, vcc
	v_lshl_or_b32 v50, v45, 2, s1
	v_lshrrev_b32_e32 v49, 6, v55
	s_waitcnt lgkmcnt(0)
	v_add_f32_e32 v44, v44, v46
	ds_bpermute_b32 v46, v133, v44
	v_mfma_f32_16x16x32_bf16 v[34:37], v[164:167], v[62:65], v[140:143]
	v_and_b32_e32 v64, 47, v54
	v_mov_b32_e32 v121, v122
	v_ashrrev_i32_e32 v51, 31, v50
	s_waitcnt lgkmcnt(0)
	v_add_f32_e32 v44, v44, v46
	v_fmamk_f32 v44, v44, 0x3c2aaaab, v197
	v_cmp_gt_f32_e64 s[38:39], s47, v44
	v_mul_f32_e32 v46, 0x4b800000, v44
	s_nop 0
	v_cndmask_b32_e64 v44, v44, v46, s[38:39]
	v_rsq_f32_e32 v44, v44
	s_nop 0
	v_mul_f32_e32 v46, 0x45800000, v44
	v_cndmask_b32_e64 v48, v44, v46, s[38:39]
	v_mad_i64_i32 v[44:45], s[6:7], v50, s9, v[0:1]
	v_mad_u64_u32 v[52:53], s[6:7], v44, s15, v[104:105]
	v_mad_i32_i24 v53, v45, s15, v53
	s_nop 0
	s_nop 0
	v_pk_mul_f32 v[56:57], v[70:71], v[48:49] op_sel_hi:[1,0]
	v_pk_mul_f32 v[54:55], v[72:73], v[48:49] op_sel_hi:[1,0]
	v_lshlrev_b32_e32 v0, 1, v0
	s_nop 0
	v_pk_mul_f32 v[44:45], v[246:247], v[56:57]
	v_pk_mul_f32 v[46:47], v[248:249], v[54:55]
	v_cvt_pk_bf16_f32 v44, v44, v45
	v_pk_mul_f32 v[56:57], v[78:79], v[48:49] op_sel_hi:[1,0]
	v_cvt_pk_bf16_f32 v45, v46, v47
	flat_store_dwordx2 v[52:53], v[44:45]
	s_nop 0
	s_nop 0
	v_pk_mul_f32 v[54:55], v[80:81], v[48:49] op_sel_hi:[1,0]
	s_nop 0
	v_pk_mul_f32 v[44:45], v[176:177], v[56:57]
	v_pk_mul_f32 v[46:47], v[178:179], v[54:55]
	v_cvt_pk_bf16_f32 v44, v44, v45
	v_pk_mul_f32 v[56:57], v[82:83], v[48:49] op_sel_hi:[1,0]
	v_cvt_pk_bf16_f32 v45, v46, v47
	flat_store_dwordx2 v[52:53], v[44:45] offset:32
	s_nop 0
	s_nop 0
	v_pk_mul_f32 v[54:55], v[84:85], v[48:49] op_sel_hi:[1,0]
	s_nop 0
	v_pk_mul_f32 v[44:45], v[180:181], v[56:57]
	v_pk_mul_f32 v[46:47], v[182:183], v[54:55]
	v_cvt_pk_bf16_f32 v44, v44, v45
	v_pk_mul_f32 v[56:57], v[86:87], v[48:49] op_sel_hi:[1,0]
	v_cvt_pk_bf16_f32 v45, v46, v47
	flat_store_dwordx2 v[52:53], v[44:45] offset:64
	s_nop 0
	s_nop 0
	v_pk_mul_f32 v[54:55], v[88:89], v[48:49] op_sel_hi:[1,0]
	s_nop 0
	v_pk_mul_f32 v[44:45], v[56:57], v[184:185]
	v_pk_mul_f32 v[46:47], v[54:55], v[186:187]
	v_cvt_pk_bf16_f32 v44, v44, v45
	v_mov_b32_e32 v54, v126
	v_cvt_pk_bf16_f32 v45, v46, v47
	flat_store_dwordx2 v[52:53], v[44:45] offset:96
	s_nop 0
	s_nop 0
	v_mov_b32_e32 v55, v128
	v_mov_b32_e32 v128, v127
	v_pk_mul_f32 v[54:55], v[48:49], v[54:55] op_sel_hi:[0,1]
	v_pk_mul_f32 v[56:57], v[48:49], v[128:129] op_sel_hi:[0,1]
	v_cvt_f32_ubyte0_e32 v49, v49
	v_mul_f32_e32 v58, v134, v49
	v_mul_f32_e32 v59, 0.15915494, v58
	v_cos_f32_e32 v58, v59
	v_sin_f32_e32 v60, v59
	v_mul_f32_e32 v59, v135, v49
	v_mul_f32_e32 v61, 0.15915494, v59
	v_cos_f32_e32 v59, v61
	v_sin_f32_e32 v61, v61
	s_nop 0
	v_pk_mul_f32 v[44:45], v[54:55], v[188:189]
	ds_bpermute_b32 v54, v133, v44
	ds_bpermute_b32 v55, v133, v45
	v_pk_mul_f32 v[46:47], v[56:57], v[190:191]
	ds_bpermute_b32 v56, v133, v46
	ds_bpermute_b32 v57, v133, v47
	s_waitcnt lgkmcnt(0)
; __device__ __forceinline__ unsigned cvt_pk_bf16(float lo, float hi) { unsigned r; asm volatile("v_cvt_pk_bf16_f32 %0, %1, %2" : "=v"(r) : "v"(lo), "v"(hi)); return r; }
; __device__ __forceinline__ bf16_t tobf(float f) { return (bf16_t)(cvt_pk_bf16(f, 0.f) & 0xffffu); }
; __device__ __forceinline__ f32x4 rope16(f32x4 v, int fq, float pos) {
;     f32x4 pr; pr[0] = __shfl_xor(v[0], 32); pr[1] = __shfl_xor(v[1], 32); pr[2] = __shfl_xor(v[2], 32); pr[3] = __shfl_xor(v[3], 32);
;     f32x4 o;
; #pragma unroll
;     for (int q = 0; q < 4; ++q) { const int f = (fq * 4 + q) & 7; const float inv = __builtin_amdgcn_exp2f(-(float)f * 1.6609640474f); float sn, cs; __sincosf(pos * inv, &sn, &cs);
;         o[q] = fq < 2 ? v[q] * cs - pr[q] * sn : pr[q] * sn + v[q] * cs; }
;     return o;
; __device__ __forceinline__ void kvproj_task(int t, int l, const float* kvnorm, const float* kgain, const bf16_t* P, const bf16_t* WUKV, bf16_t* KB, bf16_t* VT, int fr, int fq) {
;     ...
;         for (int cb = 0; cb < 6; ++cb) { const f32x4 kg = *(const f32x4*)(kgain + l * 96 + cb * 16 + fq * 4); f32x4 v = (cb < 4 ? acc[tb][cb < 4 ? cb : 0] : kr[tb][cb >= 4 ? cb - 4 : 0]) * rh * kg;
;             if (cb >= 4) { const f32x4 rv = rope16(v, fq, (float)(cb == 4 ? (tpos >> 6) : (tpos & 63))); if (!isc) v = rv; }
;             u32x2 w; w.x = cvt_pk_bf16(v[0], v[1]); w.y = cvt_pk_bf16(v[2], v[3]);
;             *(u32x2*)(kdst + cb * 16 + fq * 4) = w; }
; #pragma unroll
;         for (int cb = 4; cb < 8; ++cb)
; #pragma unroll
;             for (int q = 0; q < 4; ++q) VT[((size_t)(b * 4 + h) * 64 + (cb - 4) * 16 + fq * 4 + q) * NKEY + key] = tobf(acc[tb][cb][q]); }
	v_pk_mul_f32 v[54:55], v[60:61], v[54:55]
	v_mul_f32_e32 v60, v136, v49
	v_mul_f32_e32 v49, v137, v49
	v_mul_f32_e32 v61, 0.15915494, v60
	v_mul_f32_e32 v49, 0.15915494, v49
	v_sin_f32_e32 v62, v61
	v_sin_f32_e32 v63, v49
	v_cos_f32_e32 v60, v61
	v_cos_f32_e32 v61, v49
	v_cndmask_b32_e64 v55, v55, -v55, s[36:37]
	v_pk_mul_f32 v[56:57], v[62:63], v[56:57]
	v_cndmask_b32_e64 v54, v54, -v54, s[36:37]
	v_cndmask_b32_e64 v57, v57, -v57, s[36:37]
	v_cndmask_b32_e64 v56, v56, -v56, s[36:37]
	v_pk_fma_f32 v[54:55], v[58:59], v[44:45], v[54:55]
	v_pk_fma_f32 v[56:57], v[60:61], v[46:47], v[56:57]
	v_cndmask_b32_e32 v44, v54, v44, vcc
	v_cndmask_b32_e32 v45, v55, v45, vcc
	v_cndmask_b32_e32 v46, v56, v46, vcc
	v_cndmask_b32_e32 v47, v57, v47, vcc
	v_cvt_pk_bf16_f32 v44, v44, v45
	v_cvt_pk_bf16_f32 v45, v46, v47
	flat_store_dwordx2 v[52:53], v[44:45] offset:128
	global_load_dwordx4 v[44:47], v[102:103], off offset:320
	v_cvt_f32_ubyte0_e32 v61, v64
	v_mul_f32_e32 v56, v134, v61
	v_pk_mul_f32 v[54:55], v[48:49], v[124:125] op_sel_hi:[0,1]
	v_mul_f32_e32 v57, 0.15915494, v56
	v_pk_mul_f32 v[48:49], v[48:49], v[120:121] op_sel_hi:[0,1]
	v_cos_f32_e32 v56, v57
	v_sin_f32_e32 v58, v57
	v_mul_f32_e32 v57, v135, v61
	v_mul_f32_e32 v59, 0.15915494, v57
	v_cos_f32_e32 v57, v59
	v_sin_f32_e32 v59, v59
	s_waitcnt vmcnt(0)
	v_pk_mul_f32 v[44:45], v[54:55], v[44:45]
	v_pk_mul_f32 v[46:47], v[48:49], v[46:47]
	ds_bpermute_b32 v48, v133, v44
	ds_bpermute_b32 v49, v133, v45
	ds_bpermute_b32 v54, v133, v46
	ds_bpermute_b32 v55, v133, v47
	s_waitcnt lgkmcnt(0)
	v_pk_mul_f32 v[48:49], v[58:59], v[48:49]
	v_mul_f32_e32 v58, v136, v61
	v_mul_f32_e32 v59, 0.15915494, v58
	v_cos_f32_e32 v58, v59
	v_sin_f32_e32 v60, v59
	v_mul_f32_e32 v59, v137, v61
	v_mul_f32_e32 v61, 0.15915494, v59
	v_cos_f32_e32 v59, v61
	v_sin_f32_e32 v61, v61
	v_cndmask_b32_e64 v49, v49, -v49, s[36:37]
	v_cndmask_b32_e64 v48, v48, -v48, s[36:37]
	v_pk_fma_f32 v[48:49], v[56:57], v[44:45], v[48:49]
	v_pk_mul_f32 v[54:55], v[60:61], v[54:55]
	v_cndmask_b32_e32 v44, v48, v44, vcc
	v_cndmask_b32_e64 v55, v55, -v55, s[36:37]
	v_cndmask_b32_e64 v54, v54, -v54, s[36:37]
	v_pk_fma_f32 v[54:55], v[58:59], v[46:47], v[54:55]
	v_cndmask_b32_e32 v45, v49, v45, vcc
	v_cndmask_b32_e32 v46, v54, v46, vcc
	v_cndmask_b32_e32 v47, v55, v47, vcc
	v_cvt_pk_bf16_f32 v44, v44, v45
	v_cvt_pk_bf16_f32 v45, v46, v47
	v_lshlrev_b64 v[46:47], 6, v[50:51]
	flat_store_dwordx2 v[52:53], v[44:45] offset:160
	v_lshl_add_u64 v[44:45], s[40:41], 0, v[0:1]
	v_or_b32_e32 v0, v46, v96
	v_mad_u64_u32 v[44:45], s[6:7], v0, s88, v[44:45]
	v_cvt_pk_bf16_f32 v46, v74, v1
	v_mad_i32_i24 v45, v47, s88, v45
	flat_store_short v[44:45], v46
	v_add_co_u32_e64 v46, s[38:39], s21, v44
	v_cvt_pk_bf16_f32 v0, v75, v1
	s_nop 1
	v_addc_co_u32_e64 v47, s[38:39], 0, v45, s[38:39]
	flat_store_short v[46:47], v0 offset:512
	v_add_co_u32_e64 v46, s[38:39], s33, v44
	v_cvt_pk_bf16_f32 v0, v76, v1
	s_nop 1
	v_addc_co_u32_e64 v47, s[38:39], 0, v45, s[38:39]
	flat_store_short v[46:47], v0 offset:1024
	v_add_co_u32_e64 v46, s[38:39], s22, v44
	v_cvt_pk_bf16_f32 v0, v77, v1
	s_nop 1
	v_addc_co_u32_e64 v47, s[38:39], 0, v45, s[38:39]
	flat_store_short v[46:47], v0 offset:1536
	v_add_co_u32_e64 v46, s[38:39], s18, v44
	v_cvt_pk_bf16_f32 v0, v66, v1
	s_nop 1
	v_addc_co_u32_e64 v47, s[38:39], 0, v45, s[38:39]
	flat_store_short v[46:47], v0
	v_add_co_u32_e64 v46, s[38:39], s23, v44
	v_cvt_pk_bf16_f32 v0, v67, v1
	s_nop 1
	v_addc_co_u32_e64 v47, s[38:39], 0, v45, s[38:39]
	flat_store_short v[46:47], v0 offset:512
	v_add_co_u32_e64 v46, s[38:39], s19, v44
	v_cvt_pk_bf16_f32 v0, v68, v1
	s_nop 1
	v_addc_co_u32_e64 v47, s[38:39], 0, v45, s[38:39]
	flat_store_short v[46:47], v0 offset:1024
	v_add_co_u32_e64 v46, s[38:39], s24, v44
	v_cvt_pk_bf16_f32 v0, v69, v1
	s_nop 1
	v_addc_co_u32_e64 v47, s[38:39], 0, v45, s[38:39]
	flat_store_short v[46:47], v0 offset:1536
	v_add_co_u32_e64 v46, s[38:39], s25, v44
	v_cvt_pk_bf16_f32 v0, v90, v1
	s_nop 1
	v_addc_co_u32_e64 v47, s[38:39], 0, v45, s[38:39]
	flat_store_short v[46:47], v0
	v_add_co_u32_e64 v46, s[38:39], s26, v44
	v_cvt_pk_bf16_f32 v0, v91, v1
	s_nop 1
	v_addc_co_u32_e64 v47, s[38:39], 0, v45, s[38:39]
	flat_store_short v[46:47], v0 offset:512
	v_add_co_u32_e64 v46, s[38:39], s27, v44
	v_cvt_pk_bf16_f32 v0, v92, v1
	s_nop 1
	v_addc_co_u32_e64 v47, s[38:39], 0, v45, s[38:39]
	flat_store_short v[46:47], v0 offset:1024
	v_add_co_u32_e64 v46, s[38:39], s42, v44
	v_cvt_pk_bf16_f32 v0, v93, v1
	s_nop 1
	v_addc_co_u32_e64 v47, s[38:39], 0, v45, s[38:39]
	flat_store_short v[46:47], v0 offset:1536
	v_add_co_u32_e64 v46, s[38:39], s43, v44
	v_cvt_pk_bf16_f32 v0, v38, v1
	s_nop 1
	v_addc_co_u32_e64 v47, s[38:39], 0, v45, s[38:39]
	v_add_co_u32_e64 v38, s[38:39], s44, v44
	flat_store_short v[46:47], v0
	v_cvt_pk_bf16_f32 v0, v39, v1
	s_nop 0
	v_addc_co_u32_e64 v39, s[38:39], 0, v45, s[38:39]
	flat_store_short v[38:39], v0 offset:512
	v_add_co_u32_e64 v38, s[38:39], s45, v44
	v_cvt_pk_bf16_f32 v0, v40, v1
	v_mul_f32_e32 v47, v32, v32
	s_nop 0
	v_addc_co_u32_e64 v39, s[38:39], 0, v45, s[38:39]
	flat_store_short v[38:39], v0 offset:1024
	v_add_co_u32_e64 v38, s[38:39], s46, v44
	v_cvt_pk_bf16_f32 v0, v41, v1
	s_nop 1
	v_addc_co_u32_e64 v39, s[38:39], 0, v45, s[38:39]
	flat_store_short v[38:39], v0 offset:1536
	v_add_u32_e32 v0, 0xffffc010, v109
	v_cndmask_b32_e32 v39, v111, v0, vcc
	v_mul_f32_e32 v0, v28, v28
	v_pk_add_f32 v[44:45], v[118:119], v[118:119] op_sel:[0,1] op_sel_hi:[1,0]
	v_and_b32_e32 v46, v39, v43
	v_mov_b32_e32 v45, v0
	v_mul_f32_e32 v0, v113, v113
	v_mul_f32_e32 v43, v29, v29
	v_mov_b32_e32 v111, v27
	v_pk_fma_f32 v[48:49], v[112:113], v[112:113], v[0:1] op_sel_hi:[1,1,0]
	v_mov_b32_e32 v109, v26
	v_pk_mul_f32 v[40:41], v[110:111], v[110:111]
	v_mov_b32_e32 v49, v43
	v_pk_fma_f32 v[40:41], v[108:109], v[108:109], v[40:41]
	v_pk_add_f32 v[44:45], v[44:45], v[48:49]
	v_pk_mul_f32 v[48:49], v[18:19], v[18:19]
	v_pk_add_f32 v[40:41], v[40:41], v[44:45]
	v_pk_mul_f32 v[44:45], v[20:21], v[20:21]
	v_mul_f32_e32 v0, v30, v30
	v_pk_mov_b32 v[50:51], v[48:49], v[44:45] op_sel:[1,0]
	v_mov_b32_e32 v49, v45
	v_pk_add_f32 v[44:45], v[50:51], v[48:49]
	v_mul_f32_e32 v43, v31, v31
	v_pk_add_f32 v[40:41], v[40:41], v[40:41] op_sel:[0,1] op_sel_hi:[1,0]
	v_pk_add_f32 v[44:45], v[44:45], v[44:45] op_sel:[0,1] op_sel_hi:[1,0]
	v_mov_b32_e32 v41, v0
	v_mov_b32_e32 v45, v43
	v_mul_f32_e32 v0, v15, v15
	v_pk_add_f32 v[40:41], v[40:41], v[44:45]
	v_pk_fma_f32 v[44:45], v[14:15], v[14:15], v[0:1] op_sel_hi:[1,1,0]
	v_mul_f32_e32 v0, v17, v17
	v_mul_f32_e32 v50, v33, v33
	v_pk_fma_f32 v[48:49], v[16:17], v[16:17], v[0:1] op_sel_hi:[1,1,0]
	v_mov_b32_e32 v45, v47
	v_mov_b32_e32 v49, v50
	v_pk_add_f32 v[44:45], v[44:45], v[48:49]
	v_add_u32_e32 v38, 0x100, v46
	v_pk_add_f32 v[40:41], v[40:41], v[44:45]
	v_cndmask_b32_e32 v0, v38, v46, vcc
	v_add_f32_e32 v40, v40, v41
	ds_bpermute_b32 v38, v132, v40
	v_ashrrev_i32_e32 v41, v42, v39
	v_mov_b32_e32 v109, v110
	s_waitcnt lgkmcnt(0)
; __device__ __forceinline__ unsigned cvt_pk_bf16(float lo, float hi) { unsigned r; asm volatile("v_cvt_pk_bf16_f32 %0, %1, %2" : "=v"(r) : "v"(lo), "v"(hi)); return r; }
; __device__ __forceinline__ void kvproj_task(int t, int l, const float* kvnorm, const float* kgain, const bf16_t* P, const bf16_t* WUKV, bf16_t* KB, bf16_t* VT, int fr, int fq) {
;     ...
;     for (int tb = 0; tb < 2; ++tb) { const int row = row0 + tb * 16, rr = isc ? row - ML : row;
;         const int b = isc ? rr >> 8 : rr >> 11, tpos = isc ? rr & 255 : rr & 2047, key = isc ? tpos : 256 + tpos;
;         float s2 = skr[tb];
; #pragma unroll
;         for (int cb = 0; cb < 4; ++cb) s2 += (acc[tb][cb][0] * acc[tb][cb][0] + acc[tb][cb][1] * acc[tb][cb][1]) + (acc[tb][cb][2] * acc[tb][cb][2] + acc[tb][cb][3] * acc[tb][cb][3]);
;         s2 += __shfl_xor(s2, 16); s2 += __shfl_xor(s2, 32);
;         const float rh = rsqrtf(s2 * (1.f / 96.f) + EPS);
;         bf16_t* kdst = KB + ((size_t)(b * 4 + h) * NKEY + key) * 96;
; #pragma unroll
;         for (int cb = 0; cb < 6; ++cb) { const f32x4 kg = *(const f32x4*)(kgain + l * 96 + cb * 16 + fq * 4); f32x4 v = (cb < 4 ? acc[tb][cb < 4 ? cb : 0] : kr[tb][cb >= 4 ? cb - 4 : 0]) * rh * kg;
;             if (cb >= 4) { const f32x4 rv = rope16(v, fq, (float)(cb == 4 ? (tpos >> 6) : (tpos & 63))); if (!isc) v = rv; }
;             u32x2 w; w.x = cvt_pk_bf16(v[0], v[1]); w.y = cvt_pk_bf16(v[2], v[3]);
;             *(u32x2*)(kdst + cb * 16 + fq * 4) = w; }
	v_add_f32_e32 v38, v40, v38
	ds_bpermute_b32 v40, v133, v38
	s_waitcnt lgkmcnt(0)
	v_add_f32_e32 v38, v38, v40
	v_fmamk_f32 v38, v38, 0x3c2aaaab, v197
	v_cmp_gt_f32_e64 s[38:39], s47, v38
	v_mul_f32_e32 v40, 0x4b800000, v38
	s_nop 0
	v_cndmask_b32_e64 v38, v38, v40, s[38:39]
	v_rsq_f32_e32 v38, v38
	s_nop 0
	v_mul_f32_e32 v40, 0x45800000, v38
	v_cndmask_b32_e64 v38, v38, v40, s[38:39]
	v_lshl_or_b32 v40, v41, 2, s1
	v_mad_i64_i32 v[42:43], s[6:7], v40, s9, v[0:1]
	v_mad_u64_u32 v[44:45], s[6:7], v42, s15, v[104:105]
	v_lshrrev_b32_e32 v42, 6, v46
	s_nop 0
	s_nop 0
	v_pk_mul_f32 v[26:27], v[26:27], v[38:39] op_sel_hi:[1,0]
	v_mad_i32_i24 v45, v43, s15, v45
	v_pk_mul_f32 v[28:29], v[28:29], v[38:39] op_sel_hi:[1,0]
	v_pk_mul_f32 v[18:19], v[18:19], v[38:39] op_sel_hi:[1,0]
	v_pk_mul_f32 v[20:21], v[20:21], v[38:39] op_sel_hi:[1,0]
	v_pk_mul_f32 v[14:15], v[14:15], v[38:39] op_sel_hi:[1,0]
	v_pk_mul_f32 v[16:17], v[16:17], v[38:39] op_sel_hi:[1,0]
	v_ashrrev_i32_e32 v41, 31, v40
	v_lshlrev_b32_e32 v0, 1, v0
	s_mul_i32 s1, s74, 56
	s_add_i32 s5, s5, s1
	s_cmpk_gt_i32 s4, 0x8ff
	s_nop 0
	v_pk_mul_f32 v[26:27], v[246:247], v[26:27]
	v_pk_mul_f32 v[28:29], v[248:249], v[28:29]
	v_cvt_pk_bf16_f32 v26, v26, v27
	s_nop 0
	v_cvt_pk_bf16_f32 v27, v28, v29
	flat_store_dwordx2 v[44:45], v[26:27]
	s_nop 0
	s_nop 0
	s_nop 0
	v_pk_mul_f32 v[18:19], v[176:177], v[18:19]
	v_pk_mul_f32 v[20:21], v[178:179], v[20:21]
	v_cvt_pk_bf16_f32 v18, v18, v19
	s_nop 0
	v_cvt_pk_bf16_f32 v19, v20, v21
	flat_store_dwordx2 v[44:45], v[18:19] offset:32
	s_nop 0
	s_nop 0
	s_nop 0
	v_pk_mul_f32 v[14:15], v[180:181], v[14:15]
	v_pk_mul_f32 v[16:17], v[182:183], v[16:17]
	v_cvt_pk_bf16_f32 v14, v14, v15
	v_pk_mul_f32 v[20:21], v[30:31], v[38:39] op_sel_hi:[1,0]
	v_cvt_pk_bf16_f32 v15, v16, v17
	flat_store_dwordx2 v[44:45], v[14:15] offset:64
	s_nop 0
	s_nop 0
	v_pk_mul_f32 v[18:19], v[32:33], v[38:39] op_sel_hi:[1,0]
	v_cvt_f32_ubyte0_e32 v31, v42
	v_mul_f32_e32 v26, v134, v31
	v_mul_f32_e32 v27, 0.15915494, v26
	v_cos_f32_e32 v26, v27
	v_sin_f32_e32 v28, v27
	v_mul_f32_e32 v27, v135, v31
	v_mul_f32_e32 v29, 0.15915494, v27
	v_cos_f32_e32 v27, v29
	v_sin_f32_e32 v29, v29
	s_nop 0
	v_pk_mul_f32 v[14:15], v[20:21], v[184:185]
	v_pk_mul_f32 v[16:17], v[18:19], v[186:187]
	v_cvt_pk_bf16_f32 v14, v14, v15
	v_mov_b32_e32 v18, v114
	v_cvt_pk_bf16_f32 v15, v16, v17
	flat_store_dwordx2 v[44:45], v[14:15] offset:96
	s_nop 0
	s_nop 0
	v_mov_b32_e32 v19, v116
	v_pk_mul_f32 v[18:19], v[38:39], v[18:19] op_sel_hi:[0,1]
	v_mov_b32_e32 v116, v115
	v_pk_mul_f32 v[20:21], v[38:39], v[116:117] op_sel_hi:[0,1]
	s_nop 0
	v_pk_mul_f32 v[14:15], v[18:19], v[188:189]
	ds_bpermute_b32 v18, v133, v14
	ds_bpermute_b32 v19, v133, v15
	v_pk_mul_f32 v[16:17], v[20:21], v[190:191]
	ds_bpermute_b32 v20, v133, v16
	ds_bpermute_b32 v21, v133, v17
	s_waitcnt lgkmcnt(0)
	v_pk_mul_f32 v[18:19], v[28:29], v[18:19]
	v_mul_f32_e32 v28, v136, v31
	v_mul_f32_e32 v29, 0.15915494, v28
	v_cos_f32_e32 v28, v29
	v_sin_f32_e32 v30, v29
	v_mul_f32_e32 v29, v137, v31
	v_mul_f32_e32 v31, 0.15915494, v29
	v_cos_f32_e32 v29, v31
	v_sin_f32_e32 v31, v31
	v_cndmask_b32_e64 v19, v19, -v19, s[36:37]
	v_cndmask_b32_e64 v18, v18, -v18, s[36:37]
	v_pk_fma_f32 v[18:19], v[26:27], v[14:15], v[18:19]
	v_pk_mul_f32 v[20:21], v[30:31], v[20:21]
	v_cndmask_b32_e32 v14, v18, v14, vcc
	v_cndmask_b32_e64 v21, v21, -v21, s[36:37]
	v_cndmask_b32_e64 v20, v20, -v20, s[36:37]
	v_pk_fma_f32 v[20:21], v[28:29], v[16:17], v[20:21]
	v_cndmask_b32_e32 v15, v19, v15, vcc
	v_cndmask_b32_e32 v16, v20, v16, vcc
	v_cndmask_b32_e32 v17, v21, v17, vcc
	v_cvt_pk_bf16_f32 v14, v14, v15
	v_cvt_pk_bf16_f32 v15, v16, v17
	flat_store_dwordx2 v[44:45], v[14:15] offset:128
	global_load_dwordx4 v[14:17], v[102:103], off offset:320
	v_and_b32_e32 v26, 63, v39
	v_cvt_f32_ubyte0_e32 v31, v26
	v_mul_f32_e32 v26, v134, v31
	v_pk_mul_f32 v[18:19], v[38:39], v[112:113] op_sel_hi:[0,1]
	v_mul_f32_e32 v27, 0.15915494, v26
	v_cos_f32_e32 v26, v27
	v_sin_f32_e32 v28, v27
	v_mul_f32_e32 v27, v135, v31
	v_mul_f32_e32 v29, 0.15915494, v27
	v_cos_f32_e32 v27, v29
	v_sin_f32_e32 v29, v29
	v_pk_mul_f32 v[20:21], v[38:39], v[108:109] op_sel_hi:[0,1]
	s_waitcnt vmcnt(0)
; __device__ __forceinline__ unsigned cvt_pk_bf16(float lo, float hi) { unsigned r; asm volatile("v_cvt_pk_bf16_f32 %0, %1, %2" : "=v"(r) : "v"(lo), "v"(hi)); return r; }
; __device__ __forceinline__ bf16_t tobf(float f) { return (bf16_t)(cvt_pk_bf16(f, 0.f) & 0xffffu); }
; __device__ __forceinline__ f32x4 rope16(f32x4 v, int fq, float pos) {
;     f32x4 pr; pr[0] = __shfl_xor(v[0], 32); pr[1] = __shfl_xor(v[1], 32); pr[2] = __shfl_xor(v[2], 32); pr[3] = __shfl_xor(v[3], 32);
;     f32x4 o;
; #pragma unroll
;     for (int q = 0; q < 4; ++q) { const int f = (fq * 4 + q) & 7; const float inv = __builtin_amdgcn_exp2f(-(float)f * 1.6609640474f); float sn, cs; __sincosf(pos * inv, &sn, &cs);
;         o[q] = fq < 2 ? v[q] * cs - pr[q] * sn : pr[q] * sn + v[q] * cs; }
;     return o;
; __device__ __forceinline__ void kvproj_task(int t, int l, const float* kvnorm, const float* kgain, const bf16_t* P, const bf16_t* WUKV, bf16_t* KB, bf16_t* VT, int fr, int fq) {
;     ...
;         for (int cb = 0; cb < 6; ++cb) { const f32x4 kg = *(const f32x4*)(kgain + l * 96 + cb * 16 + fq * 4); f32x4 v = (cb < 4 ? acc[tb][cb < 4 ? cb : 0] : kr[tb][cb >= 4 ? cb - 4 : 0]) * rh * kg;
;             if (cb >= 4) { const f32x4 rv = rope16(v, fq, (float)(cb == 4 ? (tpos >> 6) : (tpos & 63))); if (!isc) v = rv; }
;             u32x2 w; w.x = cvt_pk_bf16(v[0], v[1]); w.y = cvt_pk_bf16(v[2], v[3]);
;             *(u32x2*)(kdst + cb * 16 + fq * 4) = w; }
; #pragma unroll
;         for (int cb = 4; cb < 8; ++cb)
; #pragma unroll
;             for (int q = 0; q < 4; ++q) VT[((size_t)(b * 4 + h) * 64 + (cb - 4) * 16 + fq * 4 + q) * NKEY + key] = tobf(acc[tb][cb][q]); }
	v_pk_mul_f32 v[14:15], v[18:19], v[14:15]
	ds_bpermute_b32 v18, v133, v14
	ds_bpermute_b32 v19, v133, v15
	v_pk_mul_f32 v[16:17], v[20:21], v[16:17]
	ds_bpermute_b32 v20, v133, v16
	ds_bpermute_b32 v21, v133, v17
	s_waitcnt lgkmcnt(0)
	v_pk_mul_f32 v[18:19], v[28:29], v[18:19]
	v_mul_f32_e32 v28, v136, v31
	v_mul_f32_e32 v29, 0.15915494, v28
	v_cos_f32_e32 v28, v29
	v_sin_f32_e32 v30, v29
	v_mul_f32_e32 v29, v137, v31
	v_mul_f32_e32 v31, 0.15915494, v29
	v_cos_f32_e32 v29, v31
	v_sin_f32_e32 v31, v31
	v_cndmask_b32_e64 v19, v19, -v19, s[36:37]
	v_cndmask_b32_e64 v18, v18, -v18, s[36:37]
	v_pk_fma_f32 v[18:19], v[26:27], v[14:15], v[18:19]
	v_pk_mul_f32 v[20:21], v[30:31], v[20:21]
	v_cndmask_b32_e32 v14, v18, v14, vcc
	v_cndmask_b32_e64 v21, v21, -v21, s[36:37]
	v_cndmask_b32_e64 v20, v20, -v20, s[36:37]
	v_pk_fma_f32 v[20:21], v[28:29], v[16:17], v[20:21]
	v_cndmask_b32_e32 v15, v19, v15, vcc
	v_cndmask_b32_e32 v16, v20, v16, vcc
	v_cndmask_b32_e32 v17, v21, v17, vcc
	v_cvt_pk_bf16_f32 v14, v14, v15
	v_cvt_pk_bf16_f32 v15, v16, v17
	v_lshlrev_b64 v[16:17], 6, v[40:41]
	flat_store_dwordx2 v[44:45], v[14:15] offset:160
	v_lshl_add_u64 v[14:15], s[40:41], 0, v[0:1]
	v_or_b32_e32 v0, v16, v96
	v_mad_u64_u32 v[14:15], s[6:7], v0, s88, v[14:15]
	v_cvt_pk_bf16_f32 v6, v6, v1
	v_mad_i32_i24 v15, v17, s88, v15
	flat_store_short v[14:15], v6
	v_add_co_u32_e32 v6, vcc, s21, v14
	v_cvt_pk_bf16_f32 v0, v7, v1
	s_nop 1
	v_addc_co_u32_e32 v7, vcc, 0, v15, vcc
	flat_store_short v[6:7], v0 offset:512
	v_add_co_u32_e32 v6, vcc, s33, v14
	v_cvt_pk_bf16_f32 v0, v8, v1
	s_nop 1
	v_addc_co_u32_e32 v7, vcc, 0, v15, vcc
	flat_store_short v[6:7], v0 offset:1024
	v_add_co_u32_e32 v6, vcc, s22, v14
	v_cvt_pk_bf16_f32 v0, v9, v1
	s_nop 1
	v_addc_co_u32_e32 v7, vcc, 0, v15, vcc
	flat_store_short v[6:7], v0 offset:1536
	v_add_co_u32_e32 v6, vcc, s18, v14
	v_cvt_pk_bf16_f32 v0, v2, v1
	s_nop 1
	v_addc_co_u32_e32 v7, vcc, 0, v15, vcc
	v_add_co_u32_e32 v2, vcc, s23, v14
	flat_store_short v[6:7], v0
	v_cvt_pk_bf16_f32 v0, v3, v1
	s_nop 0
	v_addc_co_u32_e32 v3, vcc, 0, v15, vcc
	flat_store_short v[2:3], v0 offset:512
	v_add_co_u32_e32 v2, vcc, s19, v14
	v_cvt_pk_bf16_f32 v0, v4, v1
	s_nop 1
	v_addc_co_u32_e32 v3, vcc, 0, v15, vcc
	flat_store_short v[2:3], v0 offset:1024
	v_add_co_u32_e32 v2, vcc, s24, v14
	v_cvt_pk_bf16_f32 v0, v5, v1
	s_nop 1
	v_addc_co_u32_e32 v3, vcc, 0, v15, vcc
	flat_store_short v[2:3], v0 offset:1536
	v_add_co_u32_e32 v2, vcc, s25, v14
	v_cvt_pk_bf16_f32 v0, v34, v1
	s_nop 1
	v_addc_co_u32_e32 v3, vcc, 0, v15, vcc
	flat_store_short v[2:3], v0
	v_add_co_u32_e32 v2, vcc, s26, v14
	v_cvt_pk_bf16_f32 v0, v35, v1
	s_nop 1
	v_addc_co_u32_e32 v3, vcc, 0, v15, vcc
	flat_store_short v[2:3], v0 offset:512
	v_add_co_u32_e32 v2, vcc, s27, v14
	v_cvt_pk_bf16_f32 v0, v36, v1
	s_nop 1
	v_addc_co_u32_e32 v3, vcc, 0, v15, vcc
	flat_store_short v[2:3], v0 offset:1024
	v_add_co_u32_e32 v2, vcc, s42, v14
	v_cvt_pk_bf16_f32 v0, v37, v1
	s_nop 1
	v_addc_co_u32_e32 v3, vcc, 0, v15, vcc
	flat_store_short v[2:3], v0 offset:1536
	v_add_co_u32_e32 v2, vcc, s43, v14
	v_cvt_pk_bf16_f32 v0, v22, v1
	s_nop 1
	v_addc_co_u32_e32 v3, vcc, 0, v15, vcc
	flat_store_short v[2:3], v0
	v_add_co_u32_e32 v2, vcc, s44, v14
	v_cvt_pk_bf16_f32 v0, v23, v1
	s_nop 1
	v_addc_co_u32_e32 v3, vcc, 0, v15, vcc
	flat_store_short v[2:3], v0 offset:512
	v_add_co_u32_e32 v2, vcc, 0x38000, v14
	v_cvt_pk_bf16_f32 v0, v24, v1
	s_nop 1
	v_addc_co_u32_e32 v3, vcc, 0, v15, vcc
	flat_store_short v[2:3], v0 offset:1024
	v_add_co_u32_e32 v2, vcc, 0x39000, v14
	v_cvt_pk_bf16_f32 v0, v25, v1
	s_nop 1
	v_addc_co_u32_e32 v3, vcc, 0, v15, vcc
	flat_store_short v[2:3], v0 offset:1536
	s_cbranch_scc0 .LBB0_427
	s_movk_i32 s90, 0x1000
